# HGRN chunk loop: L2 touch prefetch of next chunk's blf/bq/bi/bg lines
# speedup vs baseline: 1.0104x; 1.0079x over previous
.LBB0_175:
	s_or_b64 exec, exec, s[42:43]
	s_waitcnt lgkmcnt(0)
	v_cndmask_b32_e64 v195, v195, 0, s[4:5]
	v_add_f32_e32 v195, v96, v195
	v_max_f32_e32 v196, 0xc2a00000, v195
	v_mul_f32_e32 v197, 0x3fb8aa3b, v196
	v_mul_f32_e32 v96, 0x3fb8aa3b, v96
	v_exp_f32_e32 v197, v197
	v_exp_f32_e32 v96, v96
	v_mul_f32_e32 v196, 0xbfb8aa3b, v196
	v_exp_f32_e32 v196, v196
	v_lshlrev_b32_e32 v194, 16, v194
	v_sub_f32_e32 v96, 1.0, v96
	v_mul_f32_e32 v194, v197, v194
	v_mul_f32_e32 v96, v96, v196
	v_bfe_u32 v196, v194, 16, 1
	v_add3_u32 v194, v194, v196, s33
	ds_write_b16_d16_hi v152, v194
	v_bfe_u32 v194, v96, 16, 1
	v_add3_u32 v96, v96, v194, s33
	v_lshrrev_b32_e32 v96, 16, v96
	ds_write_b16 v152, v96 offset:17408
	ds_write_b16 v161, v96 offset:34816
	v_add_f32_e32 v96, v97, v195
	v_max_f32_e32 v194, 0xc2a00000, v96
	v_mul_f32_e32 v195, 0x3fb8aa3b, v194
	v_mul_f32_e32 v97, 0x3fb8aa3b, v97
	v_exp_f32_e32 v195, v195
	v_exp_f32_e32 v97, v97
	v_mul_f32_e32 v194, 0xbfb8aa3b, v194
	v_exp_f32_e32 v194, v194
	v_lshlrev_b32_e32 v193, 16, v193
	v_sub_f32_e32 v97, 1.0, v97
	v_mul_f32_e32 v193, v195, v193
	v_mul_f32_e32 v97, v97, v194
	v_bfe_u32 v194, v193, 16, 1
	v_add3_u32 v193, v193, v194, s33
	ds_write_b16_d16_hi v152, v193 offset:272
	v_bfe_u32 v193, v97, 16, 1
	v_add3_u32 v97, v97, v193, s33
	v_lshrrev_b32_e32 v97, 16, v97
	v_add_f32_e32 v96, v94, v96
	ds_write_b16 v152, v97 offset:17680
	ds_write_b16 v161, v97 offset:34818
	v_max_f32_e32 v97, 0xc2a00000, v96
	v_mul_f32_e32 v193, 0x3fb8aa3b, v97
	v_mul_f32_e32 v94, 0x3fb8aa3b, v94
	v_exp_f32_e32 v193, v193
	v_exp_f32_e32 v94, v94
	v_mul_f32_e32 v97, 0xbfb8aa3b, v97
	v_exp_f32_e32 v97, v97
	v_lshlrev_b32_e32 v192, 16, v192
	v_sub_f32_e32 v94, 1.0, v94
	v_mul_f32_e32 v192, v193, v192
	v_mul_f32_e32 v94, v94, v97
	v_bfe_u32 v97, v192, 16, 1
	v_add3_u32 v97, v192, v97, s33
	ds_write_b16_d16_hi v152, v97 offset:544
	v_bfe_u32 v97, v94, 16, 1
	v_add3_u32 v94, v94, v97, s33
	v_lshrrev_b32_e32 v94, 16, v94
	ds_write_b16 v152, v94 offset:17952
	ds_write_b16 v161, v94 offset:34820
	v_add_f32_e32 v94, v95, v96
	v_max_f32_e32 v96, 0xc2a00000, v94
	v_mul_f32_e32 v97, 0x3fb8aa3b, v96
	v_mul_f32_e32 v95, 0x3fb8aa3b, v95
	v_exp_f32_e32 v97, v97
	v_exp_f32_e32 v95, v95
	v_mul_f32_e32 v96, 0xbfb8aa3b, v96
	v_exp_f32_e32 v96, v96
	v_lshlrev_b32_e32 v191, 16, v191
	v_sub_f32_e32 v95, 1.0, v95
	v_mul_f32_e32 v97, v97, v191
	v_mul_f32_e32 v95, v95, v96
	v_bfe_u32 v96, v97, 16, 1
	v_add3_u32 v96, v97, v96, s33
	ds_write_b16_d16_hi v152, v96 offset:816
	v_bfe_u32 v96, v95, 16, 1
	v_add3_u32 v95, v95, v96, s33
	v_lshrrev_b32_e32 v95, 16, v95
	v_add_f32_e32 v94, v92, v94
	ds_write_b16 v152, v95 offset:18224
	ds_write_b16 v161, v95 offset:34822
	v_max_f32_e32 v95, 0xc2a00000, v94
	v_mul_f32_e32 v96, 0x3fb8aa3b, v95
	v_mul_f32_e32 v92, 0x3fb8aa3b, v92
	v_exp_f32_e32 v96, v96
	v_exp_f32_e32 v92, v92
	v_mul_f32_e32 v95, 0xbfb8aa3b, v95
	v_exp_f32_e32 v95, v95
	v_lshlrev_b32_e32 v97, 16, v190
	v_sub_f32_e32 v92, 1.0, v92
	v_mul_f32_e32 v96, v96, v97
	v_mul_f32_e32 v92, v92, v95
	v_bfe_u32 v95, v96, 16, 1
	v_add3_u32 v95, v96, v95, s33
	ds_write_b16_d16_hi v152, v95 offset:1088
	v_bfe_u32 v95, v92, 16, 1
	v_add3_u32 v92, v92, v95, s33
	v_lshrrev_b32_e32 v92, 16, v92
	ds_write_b16 v152, v92 offset:18496
	ds_write_b16 v161, v92 offset:34824
	v_add_f32_e32 v92, v93, v94
	v_max_f32_e32 v94, 0xc2a00000, v92
	v_mul_f32_e32 v95, 0x3fb8aa3b, v94
	v_mul_f32_e32 v93, 0x3fb8aa3b, v93
	v_exp_f32_e32 v95, v95
	v_exp_f32_e32 v93, v93
	v_mul_f32_e32 v94, 0xbfb8aa3b, v94
	v_exp_f32_e32 v94, v94
	v_lshlrev_b32_e32 v96, 16, v189
	v_sub_f32_e32 v93, 1.0, v93
	v_mul_f32_e32 v95, v95, v96
	v_mul_f32_e32 v93, v93, v94
	v_bfe_u32 v94, v95, 16, 1
	v_add3_u32 v94, v95, v94, s33
	ds_write_b16_d16_hi v152, v94 offset:1360
	v_bfe_u32 v94, v93, 16, 1
	v_add3_u32 v93, v93, v94, s33
	v_lshrrev_b32_e32 v93, 16, v93
	v_add_f32_e32 v92, v90, v92
	ds_write_b16 v152, v93 offset:18768
	ds_write_b16 v161, v93 offset:34826
	v_max_f32_e32 v93, 0xc2a00000, v92
	v_mul_f32_e32 v94, 0x3fb8aa3b, v93
	v_mul_f32_e32 v90, 0x3fb8aa3b, v90
	v_exp_f32_e32 v94, v94
	v_exp_f32_e32 v90, v90
	v_mul_f32_e32 v93, 0xbfb8aa3b, v93
	v_exp_f32_e32 v93, v93
	v_lshlrev_b32_e32 v95, 16, v188
	v_sub_f32_e32 v90, 1.0, v90
	v_mul_f32_e32 v94, v94, v95
	v_mul_f32_e32 v90, v90, v93
	v_bfe_u32 v93, v94, 16, 1
	v_add3_u32 v93, v94, v93, s33
	ds_write_b16_d16_hi v152, v93 offset:1632
	v_bfe_u32 v93, v90, 16, 1
	v_add3_u32 v90, v90, v93, s33
	v_lshrrev_b32_e32 v90, 16, v90
	ds_write_b16 v152, v90 offset:19040
	ds_write_b16 v161, v90 offset:34828
	v_add_f32_e32 v90, v91, v92
	v_max_f32_e32 v92, 0xc2a00000, v90
	v_mul_f32_e32 v93, 0x3fb8aa3b, v92
	v_mul_f32_e32 v91, 0x3fb8aa3b, v91
	v_exp_f32_e32 v93, v93
	v_exp_f32_e32 v91, v91
	v_mul_f32_e32 v92, 0xbfb8aa3b, v92
	v_exp_f32_e32 v92, v92
	v_lshlrev_b32_e32 v94, 16, v186
	v_sub_f32_e32 v91, 1.0, v91
	v_mul_f32_e32 v93, v93, v94
	v_mul_f32_e32 v91, v91, v92
	v_bfe_u32 v92, v93, 16, 1
	v_add3_u32 v92, v93, v92, s33
	ds_write_b16_d16_hi v152, v92 offset:1904
	v_bfe_u32 v92, v91, 16, 1
	v_add3_u32 v91, v91, v92, s33
	v_lshrrev_b32_e32 v91, 16, v91
	v_add_f32_e32 v90, v88, v90
	ds_write_b16 v152, v91 offset:19312
	ds_write_b16 v161, v91 offset:34830
	v_max_f32_e32 v91, 0xc2a00000, v90
	v_mul_f32_e32 v92, 0x3fb8aa3b, v91
	v_mul_f32_e32 v88, 0x3fb8aa3b, v88
	v_exp_f32_e32 v92, v92
	v_exp_f32_e32 v88, v88
	v_mul_f32_e32 v91, 0xbfb8aa3b, v91
	v_exp_f32_e32 v91, v91
	v_lshlrev_b32_e32 v93, 16, v187
	v_sub_f32_e32 v88, 1.0, v88
	v_mul_f32_e32 v92, v92, v93
	v_mul_f32_e32 v88, v88, v91
	v_bfe_u32 v91, v92, 16, 1
	v_add3_u32 v91, v92, v91, s33
	ds_write_b16_d16_hi v152, v91 offset:2176
	v_bfe_u32 v91, v88, 16, 1
	v_add3_u32 v88, v88, v91, s33
	v_lshrrev_b32_e32 v88, 16, v88
	ds_write_b16 v152, v88 offset:19584
	ds_write_b16 v161, v88 offset:34832
	v_add_f32_e32 v88, v89, v90
	v_max_f32_e32 v90, 0xc2a00000, v88
	v_mul_f32_e32 v91, 0x3fb8aa3b, v90
	v_mul_f32_e32 v89, 0x3fb8aa3b, v89
	v_exp_f32_e32 v91, v91
	v_exp_f32_e32 v89, v89
	v_mul_f32_e32 v90, 0xbfb8aa3b, v90
	v_exp_f32_e32 v90, v90
	v_lshlrev_b32_e32 v92, 16, v185
	v_sub_f32_e32 v89, 1.0, v89
	v_mul_f32_e32 v91, v91, v92
	v_mul_f32_e32 v89, v89, v90
	v_bfe_u32 v90, v91, 16, 1
	v_add3_u32 v90, v91, v90, s33
	ds_write_b16_d16_hi v152, v90 offset:2448
	v_bfe_u32 v90, v89, 16, 1
	v_add3_u32 v89, v89, v90, s33
	v_lshrrev_b32_e32 v89, 16, v89
	v_add_f32_e32 v88, v86, v88
	ds_write_b16 v152, v89 offset:19856
	ds_write_b16 v161, v89 offset:34834
	v_max_f32_e32 v89, 0xc2a00000, v88
	v_mul_f32_e32 v90, 0x3fb8aa3b, v89
	v_mul_f32_e32 v86, 0x3fb8aa3b, v86
	v_exp_f32_e32 v90, v90
	v_exp_f32_e32 v86, v86
	v_mul_f32_e32 v89, 0xbfb8aa3b, v89
	v_exp_f32_e32 v89, v89
	v_lshlrev_b32_e32 v91, 16, v184
	v_sub_f32_e32 v86, 1.0, v86
	v_mul_f32_e32 v90, v90, v91
	v_mul_f32_e32 v86, v86, v89
	v_bfe_u32 v89, v90, 16, 1
	v_add3_u32 v89, v90, v89, s33
	ds_write_b16_d16_hi v152, v89 offset:2720
	v_bfe_u32 v89, v86, 16, 1
	v_add3_u32 v86, v86, v89, s33
	v_lshrrev_b32_e32 v86, 16, v86
	ds_write_b16 v152, v86 offset:20128
	ds_write_b16 v161, v86 offset:34836
	v_add_f32_e32 v86, v87, v88
	v_max_f32_e32 v88, 0xc2a00000, v86
	v_mul_f32_e32 v89, 0x3fb8aa3b, v88
	v_mul_f32_e32 v87, 0x3fb8aa3b, v87
	v_exp_f32_e32 v89, v89
	v_exp_f32_e32 v87, v87
	v_mul_f32_e32 v88, 0xbfb8aa3b, v88
	v_exp_f32_e32 v88, v88
	v_lshlrev_b32_e32 v90, 16, v183
	v_sub_f32_e32 v87, 1.0, v87
	v_mul_f32_e32 v89, v89, v90
	v_mul_f32_e32 v87, v87, v88
	v_bfe_u32 v88, v89, 16, 1
	v_add3_u32 v88, v89, v88, s33
	ds_write_b16_d16_hi v152, v88 offset:2992
	v_bfe_u32 v88, v87, 16, 1
	v_add3_u32 v87, v87, v88, s33
	v_lshrrev_b32_e32 v87, 16, v87
	v_add_f32_e32 v86, v84, v86
	ds_write_b16 v152, v87 offset:20400
	ds_write_b16 v161, v87 offset:34838
	v_max_f32_e32 v87, 0xc2a00000, v86
	v_mul_f32_e32 v88, 0x3fb8aa3b, v87
	v_mul_f32_e32 v84, 0x3fb8aa3b, v84
	v_exp_f32_e32 v88, v88
	v_exp_f32_e32 v84, v84
	v_mul_f32_e32 v87, 0xbfb8aa3b, v87
	v_exp_f32_e32 v87, v87
	v_lshlrev_b32_e32 v89, 16, v182
	v_sub_f32_e32 v84, 1.0, v84
	v_mul_f32_e32 v88, v88, v89
	v_mul_f32_e32 v84, v84, v87
	v_bfe_u32 v87, v88, 16, 1
	v_add3_u32 v87, v88, v87, s33
	ds_write_b16_d16_hi v152, v87 offset:3264
	v_bfe_u32 v87, v84, 16, 1
	v_add3_u32 v84, v84, v87, s33
	v_lshrrev_b32_e32 v84, 16, v84
	ds_write_b16 v152, v84 offset:20672
	ds_write_b16 v161, v84 offset:34840
	v_add_f32_e32 v84, v85, v86
	v_max_f32_e32 v86, 0xc2a00000, v84
	v_mul_f32_e32 v87, 0x3fb8aa3b, v86
	v_mul_f32_e32 v85, 0x3fb8aa3b, v85
	v_exp_f32_e32 v87, v87
	v_exp_f32_e32 v85, v85
	v_mul_f32_e32 v86, 0xbfb8aa3b, v86
	v_exp_f32_e32 v86, v86
	v_lshlrev_b32_e32 v88, 16, v181
	v_sub_f32_e32 v85, 1.0, v85
	v_mul_f32_e32 v87, v87, v88
	v_mul_f32_e32 v85, v85, v86
	v_bfe_u32 v86, v87, 16, 1
	v_add3_u32 v86, v87, v86, s33
	ds_write_b16_d16_hi v152, v86 offset:3536
	v_bfe_u32 v86, v85, 16, 1
	v_add3_u32 v85, v85, v86, s33
	v_lshrrev_b32_e32 v85, 16, v85
	v_add_f32_e32 v84, v82, v84
	ds_write_b16 v152, v85 offset:20944
	ds_write_b16 v161, v85 offset:34842
	v_max_f32_e32 v85, 0xc2a00000, v84
	v_mul_f32_e32 v86, 0x3fb8aa3b, v85
	v_mul_f32_e32 v82, 0x3fb8aa3b, v82
	v_exp_f32_e32 v86, v86
	v_exp_f32_e32 v82, v82
	v_mul_f32_e32 v85, 0xbfb8aa3b, v85
	v_exp_f32_e32 v85, v85
	v_lshlrev_b32_e32 v87, 16, v180
	v_sub_f32_e32 v82, 1.0, v82
	v_mul_f32_e32 v86, v86, v87
	v_mul_f32_e32 v82, v82, v85
	v_bfe_u32 v85, v86, 16, 1
	v_add3_u32 v85, v86, v85, s33
	ds_write_b16_d16_hi v152, v85 offset:3808
	v_bfe_u32 v85, v82, 16, 1
	v_add3_u32 v82, v82, v85, s33
	v_lshrrev_b32_e32 v82, 16, v82
	ds_write_b16 v152, v82 offset:21216
	ds_write_b16 v161, v82 offset:34844
	v_add_f32_e32 v82, v83, v84
	v_max_f32_e32 v84, 0xc2a00000, v82
	v_mul_f32_e32 v85, 0x3fb8aa3b, v84
	v_mul_f32_e32 v83, 0x3fb8aa3b, v83
	v_exp_f32_e32 v85, v85
	v_exp_f32_e32 v83, v83
	v_mul_f32_e32 v84, 0xbfb8aa3b, v84
	v_exp_f32_e32 v84, v84
	v_lshlrev_b32_e32 v86, 16, v178
	v_sub_f32_e32 v83, 1.0, v83
	v_mul_f32_e32 v85, v85, v86
	v_mul_f32_e32 v83, v83, v84
	v_bfe_u32 v84, v85, 16, 1
	v_add3_u32 v84, v85, v84, s33
	ds_write_b16_d16_hi v152, v84 offset:4080
	v_bfe_u32 v84, v83, 16, 1
	v_add3_u32 v83, v83, v84, s33
	v_lshrrev_b32_e32 v83, 16, v83
	v_add_f32_e32 v82, v80, v82
	ds_write_b16 v152, v83 offset:21488
	ds_write_b16 v161, v83 offset:34846
	v_max_f32_e32 v83, 0xc2a00000, v82
	v_mul_f32_e32 v84, 0x3fb8aa3b, v83
	v_mul_f32_e32 v80, 0x3fb8aa3b, v80
	v_exp_f32_e32 v84, v84
	v_exp_f32_e32 v80, v80
	v_mul_f32_e32 v83, 0xbfb8aa3b, v83
	v_exp_f32_e32 v83, v83
	v_lshlrev_b32_e32 v85, 16, v179
	v_sub_f32_e32 v80, 1.0, v80
	v_mul_f32_e32 v84, v84, v85
	v_mul_f32_e32 v80, v80, v83
	v_bfe_u32 v83, v84, 16, 1
	v_add3_u32 v83, v84, v83, s33
	ds_write_b16_d16_hi v152, v83 offset:4352
	v_bfe_u32 v83, v80, 16, 1
	v_add3_u32 v80, v80, v83, s33
	v_lshrrev_b32_e32 v80, 16, v80
	ds_write_b16 v152, v80 offset:21760
	ds_write_b16 v161, v80 offset:34848
	v_add_f32_e32 v80, v81, v82
	v_max_f32_e32 v82, 0xc2a00000, v80
	v_mul_f32_e32 v83, 0x3fb8aa3b, v82
	v_mul_f32_e32 v81, 0x3fb8aa3b, v81
	v_exp_f32_e32 v83, v83
	v_exp_f32_e32 v81, v81
	v_mul_f32_e32 v82, 0xbfb8aa3b, v82
	v_exp_f32_e32 v82, v82
	v_lshlrev_b32_e32 v84, 16, v177
	v_sub_f32_e32 v81, 1.0, v81
	v_mul_f32_e32 v83, v83, v84
	v_mul_f32_e32 v81, v81, v82
	v_bfe_u32 v82, v83, 16, 1
	v_add3_u32 v82, v83, v82, s33
	ds_write_b16_d16_hi v152, v82 offset:4624
	v_bfe_u32 v82, v81, 16, 1
	v_add3_u32 v81, v81, v82, s33
	v_lshrrev_b32_e32 v81, 16, v81
	v_add_f32_e32 v80, v78, v80
	ds_write_b16 v152, v81 offset:22032
	ds_write_b16 v161, v81 offset:34850
	v_max_f32_e32 v81, 0xc2a00000, v80
	v_mul_f32_e32 v82, 0x3fb8aa3b, v81
	v_mul_f32_e32 v78, 0x3fb8aa3b, v78
	v_exp_f32_e32 v82, v82
	v_exp_f32_e32 v78, v78
	v_mul_f32_e32 v81, 0xbfb8aa3b, v81
	v_exp_f32_e32 v81, v81
	v_lshlrev_b32_e32 v83, 16, v176
	v_sub_f32_e32 v78, 1.0, v78
	v_mul_f32_e32 v82, v82, v83
	v_mul_f32_e32 v78, v78, v81
	v_bfe_u32 v81, v82, 16, 1
	v_add3_u32 v81, v82, v81, s33
	ds_write_b16_d16_hi v152, v81 offset:4896
	v_bfe_u32 v81, v78, 16, 1
	v_add3_u32 v78, v78, v81, s33
	v_lshrrev_b32_e32 v78, 16, v78
	ds_write_b16 v152, v78 offset:22304
	ds_write_b16 v161, v78 offset:34852
	v_add_f32_e32 v78, v79, v80
	v_max_f32_e32 v80, 0xc2a00000, v78
	v_mul_f32_e32 v81, 0x3fb8aa3b, v80
	v_mul_f32_e32 v79, 0x3fb8aa3b, v79
	v_exp_f32_e32 v81, v81
	v_exp_f32_e32 v79, v79
	v_mul_f32_e32 v80, 0xbfb8aa3b, v80
	v_exp_f32_e32 v80, v80
	v_lshlrev_b32_e32 v82, 16, v175
	v_sub_f32_e32 v79, 1.0, v79
	v_mul_f32_e32 v81, v81, v82
	v_mul_f32_e32 v79, v79, v80
	v_bfe_u32 v80, v81, 16, 1
	v_add3_u32 v80, v81, v80, s33
	ds_write_b16_d16_hi v152, v80 offset:5168
	v_bfe_u32 v80, v79, 16, 1
	v_add3_u32 v79, v79, v80, s33
	v_lshrrev_b32_e32 v79, 16, v79
	v_add_f32_e32 v78, v76, v78
	ds_write_b16 v152, v79 offset:22576
	ds_write_b16 v161, v79 offset:34854
	v_max_f32_e32 v79, 0xc2a00000, v78
	v_mul_f32_e32 v80, 0x3fb8aa3b, v79
	v_mul_f32_e32 v76, 0x3fb8aa3b, v76
	v_exp_f32_e32 v80, v80
	v_exp_f32_e32 v76, v76
	v_mul_f32_e32 v79, 0xbfb8aa3b, v79
	v_exp_f32_e32 v79, v79
	v_lshlrev_b32_e32 v81, 16, v125
	v_sub_f32_e32 v76, 1.0, v76
	v_mul_f32_e32 v80, v80, v81
	v_mul_f32_e32 v76, v76, v79
	v_bfe_u32 v79, v80, 16, 1
	v_add3_u32 v79, v80, v79, s33
	ds_write_b16_d16_hi v152, v79 offset:5440
	v_bfe_u32 v79, v76, 16, 1
	v_add3_u32 v76, v76, v79, s33
	v_lshrrev_b32_e32 v76, 16, v76
	ds_write_b16 v152, v76 offset:22848
	ds_write_b16 v161, v76 offset:34856
	v_add_f32_e32 v76, v77, v78
	v_max_f32_e32 v78, 0xc2a00000, v76
	v_mul_f32_e32 v79, 0x3fb8aa3b, v78
	v_mul_f32_e32 v77, 0x3fb8aa3b, v77
	v_exp_f32_e32 v79, v79
	v_exp_f32_e32 v77, v77
	v_mul_f32_e32 v78, 0xbfb8aa3b, v78
	v_exp_f32_e32 v78, v78
	v_lshlrev_b32_e32 v80, 16, v124
	v_sub_f32_e32 v77, 1.0, v77
	v_mul_f32_e32 v79, v79, v80
	v_mul_f32_e32 v77, v77, v78
	v_bfe_u32 v78, v79, 16, 1
	v_add3_u32 v78, v79, v78, s33
	ds_write_b16_d16_hi v152, v78 offset:5712
	v_bfe_u32 v78, v77, 16, 1
	v_add3_u32 v77, v77, v78, s33
	v_lshrrev_b32_e32 v77, 16, v77
	v_add_f32_e32 v76, v74, v76
	ds_write_b16 v152, v77 offset:23120
	ds_write_b16 v161, v77 offset:34858
	v_max_f32_e32 v77, 0xc2a00000, v76
	v_mul_f32_e32 v78, 0x3fb8aa3b, v77
	v_mul_f32_e32 v74, 0x3fb8aa3b, v74
	v_exp_f32_e32 v78, v78
	v_exp_f32_e32 v74, v74
	v_mul_f32_e32 v77, 0xbfb8aa3b, v77
	v_exp_f32_e32 v77, v77
	v_lshlrev_b32_e32 v79, 16, v123
	v_sub_f32_e32 v74, 1.0, v74
	v_mul_f32_e32 v78, v78, v79
	v_mul_f32_e32 v74, v74, v77
	v_bfe_u32 v77, v78, 16, 1
	v_add3_u32 v77, v78, v77, s33
	ds_write_b16_d16_hi v152, v77 offset:5984
	v_bfe_u32 v77, v74, 16, 1
	v_add3_u32 v74, v74, v77, s33
	v_lshrrev_b32_e32 v74, 16, v74
	ds_write_b16 v152, v74 offset:23392
	ds_write_b16 v161, v74 offset:34860
	v_add_f32_e32 v74, v75, v76
	v_max_f32_e32 v76, 0xc2a00000, v74
	v_mul_f32_e32 v77, 0x3fb8aa3b, v76
	v_mul_f32_e32 v75, 0x3fb8aa3b, v75
	v_exp_f32_e32 v77, v77
	v_exp_f32_e32 v75, v75
	v_mul_f32_e32 v76, 0xbfb8aa3b, v76
	v_exp_f32_e32 v76, v76
	v_lshlrev_b32_e32 v78, 16, v105
	v_sub_f32_e32 v75, 1.0, v75
	v_mul_f32_e32 v77, v77, v78
	v_mul_f32_e32 v75, v75, v76
	v_bfe_u32 v76, v77, 16, 1
	v_add3_u32 v76, v77, v76, s33
	ds_write_b16_d16_hi v152, v76 offset:6256
	v_bfe_u32 v76, v75, 16, 1
	v_add3_u32 v75, v75, v76, s33
	v_lshrrev_b32_e32 v75, 16, v75
	v_add_f32_e32 v74, v72, v74
	ds_write_b16 v152, v75 offset:23664
	ds_write_b16 v161, v75 offset:34862
	v_max_f32_e32 v75, 0xc2a00000, v74
	v_mul_f32_e32 v76, 0x3fb8aa3b, v75
	v_mul_f32_e32 v72, 0x3fb8aa3b, v72
	v_exp_f32_e32 v76, v76
	v_exp_f32_e32 v72, v72
	v_mul_f32_e32 v75, 0xbfb8aa3b, v75
	v_exp_f32_e32 v75, v75
	v_lshlrev_b32_e32 v77, 16, v122
	v_sub_f32_e32 v72, 1.0, v72
	v_mul_f32_e32 v76, v76, v77
	v_mul_f32_e32 v72, v72, v75
	v_bfe_u32 v75, v76, 16, 1
	v_add3_u32 v75, v76, v75, s33
	ds_write_b16_d16_hi v152, v75 offset:6528
	v_bfe_u32 v75, v72, 16, 1
	v_add3_u32 v72, v72, v75, s33
	v_lshrrev_b32_e32 v72, 16, v72
	ds_write_b16 v152, v72 offset:23936
	ds_write_b16 v161, v72 offset:34864
	v_add_f32_e32 v72, v73, v74
	v_max_f32_e32 v74, 0xc2a00000, v72
	v_mul_f32_e32 v75, 0x3fb8aa3b, v74
	v_mul_f32_e32 v73, 0x3fb8aa3b, v73
	v_exp_f32_e32 v75, v75
	v_exp_f32_e32 v73, v73
	v_mul_f32_e32 v74, 0xbfb8aa3b, v74
	v_exp_f32_e32 v74, v74
	v_lshlrev_b32_e32 v76, 16, v104
	v_sub_f32_e32 v73, 1.0, v73
	v_mul_f32_e32 v75, v75, v76
	v_mul_f32_e32 v73, v73, v74
	v_bfe_u32 v74, v75, 16, 1
	v_add3_u32 v74, v75, v74, s33
	ds_write_b16_d16_hi v152, v74 offset:6800
	v_bfe_u32 v74, v73, 16, 1
	v_add3_u32 v73, v73, v74, s33
	v_lshrrev_b32_e32 v73, 16, v73
	v_add_f32_e32 v72, v70, v72
	ds_write_b16 v152, v73 offset:24208
	ds_write_b16 v161, v73 offset:34866
	v_max_f32_e32 v73, 0xc2a00000, v72
	v_mul_f32_e32 v74, 0x3fb8aa3b, v73
	v_mul_f32_e32 v70, 0x3fb8aa3b, v70
	v_exp_f32_e32 v74, v74
	v_exp_f32_e32 v70, v70
	v_mul_f32_e32 v73, 0xbfb8aa3b, v73
	v_exp_f32_e32 v73, v73
	v_lshlrev_b32_e32 v75, 16, v103
	v_sub_f32_e32 v70, 1.0, v70
	v_mul_f32_e32 v74, v74, v75
	v_mul_f32_e32 v70, v70, v73
	v_bfe_u32 v73, v74, 16, 1
	v_add3_u32 v73, v74, v73, s33
	ds_write_b16_d16_hi v152, v73 offset:7072
	v_bfe_u32 v73, v70, 16, 1
	v_add3_u32 v70, v70, v73, s33
	v_lshrrev_b32_e32 v70, 16, v70
	ds_write_b16 v152, v70 offset:24480
	ds_write_b16 v161, v70 offset:34868
	v_add_f32_e32 v70, v71, v72
	v_max_f32_e32 v72, 0xc2a00000, v70
	v_mul_f32_e32 v73, 0x3fb8aa3b, v72
	v_mul_f32_e32 v71, 0x3fb8aa3b, v71
	v_exp_f32_e32 v73, v73
	v_exp_f32_e32 v71, v71
	v_mul_f32_e32 v72, 0xbfb8aa3b, v72
	v_exp_f32_e32 v72, v72
	v_lshlrev_b32_e32 v74, 16, v102
	v_sub_f32_e32 v71, 1.0, v71
	v_mul_f32_e32 v73, v73, v74
	v_mul_f32_e32 v71, v71, v72
	v_bfe_u32 v72, v73, 16, 1
	v_add3_u32 v72, v73, v72, s33
	ds_write_b16_d16_hi v152, v72 offset:7344
	v_bfe_u32 v72, v71, 16, 1
	v_add3_u32 v71, v71, v72, s33
	v_lshrrev_b32_e32 v71, 16, v71
	v_add_f32_e32 v70, v68, v70
	ds_write_b16 v152, v71 offset:24752
	ds_write_b16 v161, v71 offset:34870
	v_max_f32_e32 v71, 0xc2a00000, v70
	v_mul_f32_e32 v72, 0x3fb8aa3b, v71
	v_mul_f32_e32 v68, 0x3fb8aa3b, v68
	v_exp_f32_e32 v72, v72
	v_exp_f32_e32 v68, v68
	v_mul_f32_e32 v71, 0xbfb8aa3b, v71
	v_exp_f32_e32 v71, v71
	v_lshlrev_b32_e32 v73, 16, v101
	v_sub_f32_e32 v68, 1.0, v68
	v_mul_f32_e32 v72, v72, v73
	v_mul_f32_e32 v68, v68, v71
	v_bfe_u32 v71, v72, 16, 1
	v_add3_u32 v71, v72, v71, s33
	ds_write_b16_d16_hi v152, v71 offset:7616
	v_bfe_u32 v71, v68, 16, 1
	v_add3_u32 v68, v68, v71, s33
	v_lshrrev_b32_e32 v68, 16, v68
	ds_write_b16 v152, v68 offset:25024
	ds_write_b16 v161, v68 offset:34872
	v_add_f32_e32 v68, v69, v70
	v_max_f32_e32 v70, 0xc2a00000, v68
	v_mul_f32_e32 v71, 0x3fb8aa3b, v70
	v_mul_f32_e32 v69, 0x3fb8aa3b, v69
	v_exp_f32_e32 v71, v71
	v_exp_f32_e32 v69, v69
	v_mul_f32_e32 v70, 0xbfb8aa3b, v70
	v_exp_f32_e32 v70, v70
	v_lshlrev_b32_e32 v72, 16, v100
	v_sub_f32_e32 v69, 1.0, v69
	v_mul_f32_e32 v71, v71, v72
	v_mul_f32_e32 v69, v69, v70
	v_bfe_u32 v70, v71, 16, 1
	v_add3_u32 v70, v71, v70, s33
	ds_write_b16_d16_hi v152, v70 offset:7888
	v_bfe_u32 v70, v69, 16, 1
	v_add3_u32 v69, v69, v70, s33
	v_lshrrev_b32_e32 v69, 16, v69
	v_add_f32_e32 v68, v66, v68
	ds_write_b16 v152, v69 offset:25296
	ds_write_b16 v161, v69 offset:34874
	v_max_f32_e32 v69, 0xc2a00000, v68
	v_mul_f32_e32 v70, 0x3fb8aa3b, v69
	v_mul_f32_e32 v66, 0x3fb8aa3b, v66
	v_exp_f32_e32 v70, v70
	v_exp_f32_e32 v66, v66
	v_mul_f32_e32 v69, 0xbfb8aa3b, v69
	v_exp_f32_e32 v69, v69
	v_lshlrev_b32_e32 v71, 16, v99
	v_sub_f32_e32 v66, 1.0, v66
	v_mul_f32_e32 v70, v70, v71
	v_mul_f32_e32 v66, v66, v69
	v_bfe_u32 v69, v70, 16, 1
	v_add3_u32 v69, v70, v69, s33
	ds_write_b16_d16_hi v152, v69 offset:8160
	v_bfe_u32 v69, v66, 16, 1
	v_add3_u32 v66, v66, v69, s33
	v_lshrrev_b32_e32 v66, 16, v66
	ds_write_b16 v152, v66 offset:25568
	ds_write_b16 v161, v66 offset:34876
	v_add_f32_e32 v66, v67, v68
	v_max_f32_e32 v66, 0xc2a00000, v66
	v_mul_f32_e32 v68, 0x3fb8aa3b, v66
	v_mul_f32_e32 v67, 0x3fb8aa3b, v67
	v_exp_f32_e32 v68, v68
	v_exp_f32_e32 v67, v67
	v_mul_f32_e32 v66, 0xbfb8aa3b, v66
	v_exp_f32_e32 v66, v66
	v_lshlrev_b32_e32 v69, 16, v98
	v_sub_f32_e32 v67, 1.0, v67
	v_mul_f32_e32 v68, v68, v69
	v_mul_f32_e32 v66, v67, v66
	v_bfe_u32 v67, v68, 16, 1
	v_add3_u32 v67, v68, v67, s33
	ds_write_b16_d16_hi v152, v67 offset:8432
	v_bfe_u32 v67, v66, 16, 1
	v_add3_u32 v66, v66, v67, s33
	v_lshrrev_b32_e32 v66, 16, v66
	ds_write_b16 v152, v66 offset:25840
	ds_write_b16 v161, v66 offset:34878
	s_waitcnt lgkmcnt(0)
	s_barrier
	ds_read_b128 v[98:101], v154 offset:17408
	ds_read_b128 v[82:85], v154 offset:26112
	ds_read_b128 v[102:105], v154 offset:8704
	ds_read_b128 v[66:69], v154
	ds_read_b128 v[122:125], v154 offset:32
	ds_read_b128 v[176:179], v154 offset:17440
	ds_read_b128 v[180:183], v154 offset:26144
	ds_read_b128 v[184:187], v154 offset:8736
	s_waitcnt lgkmcnt(5)
	v_mfma_f32_32x32x16_bf16 v[82:97], v[82:85], v[102:105], 0
	s_waitcnt lgkmcnt(4)
	v_mfma_f32_32x32x16_bf16 v[66:81], v[98:101], v[66:69], 0
	s_waitcnt lgkmcnt(0)
	v_mfma_f32_32x32x16_bf16 v[82:97], v[180:183], v[184:187], v[82:97]
	v_mfma_f32_32x32x16_bf16 v[66:81], v[176:179], v[122:125], v[66:81]
	ds_read_b128 v[122:125], v154 offset:17472
	ds_read_b128 v[180:183], v154 offset:26176
	ds_read_b128 v[188:191], v154 offset:64
	ds_read_b128 v[192:195], v154 offset:8768
	s_waitcnt lgkmcnt(0)
	v_mfma_f32_32x32x16_bf16 v[82:97], v[180:183], v[192:195], v[82:97]
	v_mfma_f32_32x32x16_bf16 v[66:81], v[122:125], v[188:191], v[66:81]
	ds_read_b128 v[180:183], v154 offset:17504
	ds_read_b128 v[188:191], v154 offset:26208
	ds_read_b128 v[196:199], v154 offset:96
	ds_read_b128 v[200:203], v154 offset:8800
	s_waitcnt lgkmcnt(0)
	v_mfma_f32_32x32x16_bf16 v[82:97], v[188:191], v[200:203], v[82:97]
	v_mfma_f32_32x32x16_bf16 v[66:81], v[180:183], v[196:199], v[66:81]
	ds_read_b128 v[188:191], v154 offset:17536
	ds_read_b128 v[196:199], v154 offset:26240
	ds_read_b128 v[204:207], v154 offset:128
	ds_read_b128 v[208:211], v154 offset:8832
	s_waitcnt lgkmcnt(0)
	v_mfma_f32_32x32x16_bf16 v[82:97], v[196:199], v[208:211], v[82:97]
	v_mfma_f32_32x32x16_bf16 v[66:81], v[188:191], v[204:207], v[66:81]
	ds_read_b128 v[196:199], v154 offset:17568
	ds_read_b128 v[204:207], v154 offset:26272
	ds_read_b128 v[212:215], v154 offset:160
	ds_read_b128 v[216:219], v154 offset:8864
	s_waitcnt lgkmcnt(0)
	v_mfma_f32_32x32x16_bf16 v[82:97], v[204:207], v[216:219], v[82:97]
	v_mfma_f32_32x32x16_bf16 v[66:81], v[196:199], v[212:215], v[66:81]
	ds_read_b128 v[204:207], v154 offset:17600
	ds_read_b128 v[212:215], v154 offset:26304
	ds_read_b128 v[220:223], v154 offset:192
	ds_read_b128 v[224:227], v154 offset:8896
	s_waitcnt lgkmcnt(0)
	v_mfma_f32_32x32x16_bf16 v[82:97], v[212:215], v[224:227], v[82:97]
	v_mfma_f32_32x32x16_bf16 v[66:81], v[204:207], v[220:223], v[66:81]
	ds_read_b128 v[212:215], v154 offset:17632
	ds_read_b128 v[220:223], v154 offset:26336
	ds_read_b128 v[228:231], v154 offset:224
	ds_read_b128 v[232:235], v154 offset:8928
	s_waitcnt lgkmcnt(0)
	v_mfma_f32_32x32x16_bf16 v[82:97], v[220:223], v[232:235], v[82:97]
	v_mfma_f32_32x32x16_bf16 v[66:81], v[212:215], v[228:231], v[66:81]
	s_nop 10
	v_cndmask_b32_e64 v175, v96, 0, s[38:39]
	v_cndmask_b32_e64 v220, v97, 0, s[6:7]
	v_cndmask_b32_e64 v221, v94, 0, s[34:35]
	v_cndmask_b32_e64 v222, v95, 0, s[36:37]
	v_cndmask_b32_e64 v223, v92, 0, s[26:27]
	v_cndmask_b32_e64 v228, v93, 0, s[28:29]
	v_cndmask_b32_e64 v229, v90, 0, s[22:23]
	v_cndmask_b32_e64 v230, v91, 0, s[24:25]
	v_mfma_f32_32x32x16_bf16 v[90:105], v[98:101], v[102:105], 0
	v_cndmask_b32_e64 v88, v88, 0, s[18:19]
	v_cndmask_b32_e64 v89, v89, 0, s[20:21]
	v_cndmask_b32_e64 v86, v86, 0, s[14:15]
	v_cndmask_b32_e64 v87, v87, 0, s[16:17]
	v_cndmask_b32_e64 v84, v84, 0, s[10:11]
	v_cndmask_b32_e64 v85, v85, 0, s[12:13]
	v_cndmask_b32_e64 v82, v82, 0, s[94:95]
	v_mfma_f32_32x32x16_bf16 v[90:105], v[176:179], v[184:187], v[90:105]
	v_cndmask_b32_e64 v83, v83, 0, s[8:9]
	v_mfma_f32_32x32x16_bf16 v[90:105], v[122:125], v[192:195], v[90:105]
	v_mfma_f32_32x32x16_bf16 v[90:105], v[180:183], v[200:203], v[90:105]
	v_mfma_f32_32x32x16_bf16 v[90:105], v[188:191], v[208:211], v[90:105]
	v_mfma_f32_32x32x16_bf16 v[90:105], v[196:199], v[216:219], v[90:105]
	v_mfma_f32_32x32x16_bf16 v[90:105], v[204:207], v[224:227], v[90:105]
	v_mfma_f32_32x32x16_bf16 v[90:105], v[212:215], v[232:235], v[90:105]
	v_cndmask_b32_e64 v66, v66, 0, s[94:95]
	v_cndmask_b32_e64 v67, v67, 0, s[8:9]
	v_cndmask_b32_e64 v190, v74, 0, s[22:23]
	v_cndmask_b32_e64 v191, v75, 0, s[24:25]
	v_and_b32_sdwa v74, v67, v169 dst_sel:DWORD dst_unused:UNUSED_PAD src0_sel:WORD_1 src1_sel:DWORD
	v_and_b32_sdwa v75, v66, v169 dst_sel:DWORD dst_unused:UNUSED_PAD src0_sel:WORD_1 src1_sel:DWORD
	v_add3_u32 v66, v66, v75, s33
	v_add3_u32 v74, v67, v74, s33
	s_nop 3
	v_and_b32_sdwa v67, v91, v169 dst_sel:DWORD dst_unused:UNUSED_PAD src0_sel:WORD_1 src1_sel:DWORD
	v_and_b32_sdwa v75, v90, v169 dst_sel:DWORD dst_unused:UNUSED_PAD src0_sel:WORD_1 src1_sel:DWORD
	v_cndmask_b32_e64 v68, v68, 0, s[10:11]
	v_cndmask_b32_e64 v69, v69, 0, s[12:13]
	v_add3_u32 v90, v90, v75, s33
	v_add3_u32 v91, v91, v67, s33
	v_and_b32_sdwa v67, v83, v169 dst_sel:DWORD dst_unused:UNUSED_PAD src0_sel:WORD_1 src1_sel:DWORD
	v_and_b32_sdwa v75, v82, v169 dst_sel:DWORD dst_unused:UNUSED_PAD src0_sel:WORD_1 src1_sel:DWORD
	v_add3_u32 v180, v82, v75, s33
	v_add3_u32 v192, v83, v67, s33
	v_and_b32_sdwa v67, v69, v169 dst_sel:DWORD dst_unused:UNUSED_PAD src0_sel:WORD_1 src1_sel:DWORD
	v_and_b32_sdwa v75, v68, v169 dst_sel:DWORD dst_unused:UNUSED_PAD src0_sel:WORD_1 src1_sel:DWORD
	v_add3_u32 v75, v68, v75, s33
	v_add3_u32 v67, v69, v67, s33
	v_and_b32_sdwa v68, v93, v169 dst_sel:DWORD dst_unused:UNUSED_PAD src0_sel:WORD_1 src1_sel:DWORD
	v_and_b32_sdwa v69, v92, v169 dst_sel:DWORD dst_unused:UNUSED_PAD src0_sel:WORD_1 src1_sel:DWORD
	v_cndmask_b32_e64 v70, v70, 0, s[14:15]
	v_cndmask_b32_e64 v71, v71, 0, s[16:17]
	v_add3_u32 v92, v92, v69, s33
	v_add3_u32 v93, v93, v68, s33
	v_and_b32_sdwa v68, v85, v169 dst_sel:DWORD dst_unused:UNUSED_PAD src0_sel:WORD_1 src1_sel:DWORD
	v_and_b32_sdwa v69, v84, v169 dst_sel:DWORD dst_unused:UNUSED_PAD src0_sel:WORD_1 src1_sel:DWORD
	v_add3_u32 v181, v84, v69, s33
	v_add3_u32 v193, v85, v68, s33
	v_and_b32_sdwa v68, v71, v169 dst_sel:DWORD dst_unused:UNUSED_PAD src0_sel:WORD_1 src1_sel:DWORD
	v_and_b32_sdwa v69, v70, v169 dst_sel:DWORD dst_unused:UNUSED_PAD src0_sel:WORD_1 src1_sel:DWORD
	v_add3_u32 v70, v70, v69, s33
	v_add3_u32 v68, v71, v68, s33
	v_and_b32_sdwa v69, v95, v169 dst_sel:DWORD dst_unused:UNUSED_PAD src0_sel:WORD_1 src1_sel:DWORD
	v_and_b32_sdwa v71, v94, v169 dst_sel:DWORD dst_unused:UNUSED_PAD src0_sel:WORD_1 src1_sel:DWORD
	v_cndmask_b32_e64 v72, v72, 0, s[18:19]
	v_cndmask_b32_e64 v73, v73, 0, s[20:21]
	v_add3_u32 v94, v94, v71, s33
	v_add3_u32 v95, v95, v69, s33
	v_and_b32_sdwa v69, v87, v169 dst_sel:DWORD dst_unused:UNUSED_PAD src0_sel:WORD_1 src1_sel:DWORD
	v_and_b32_sdwa v71, v86, v169 dst_sel:DWORD dst_unused:UNUSED_PAD src0_sel:WORD_1 src1_sel:DWORD
	v_add3_u32 v182, v86, v71, s33
	v_add3_u32 v194, v87, v69, s33
	v_and_b32_sdwa v69, v73, v169 dst_sel:DWORD dst_unused:UNUSED_PAD src0_sel:WORD_1 src1_sel:DWORD
	v_and_b32_sdwa v71, v72, v169 dst_sel:DWORD dst_unused:UNUSED_PAD src0_sel:WORD_1 src1_sel:DWORD
	v_add3_u32 v71, v72, v71, s33
	v_add3_u32 v69, v73, v69, s33
	v_and_b32_sdwa v72, v97, v169 dst_sel:DWORD dst_unused:UNUSED_PAD src0_sel:WORD_1 src1_sel:DWORD
	v_and_b32_sdwa v73, v96, v169 dst_sel:DWORD dst_unused:UNUSED_PAD src0_sel:WORD_1 src1_sel:DWORD
	v_add3_u32 v86, v96, v73, s33
	v_add3_u32 v87, v97, v72, s33
	v_and_b32_sdwa v72, v89, v169 dst_sel:DWORD dst_unused:UNUSED_PAD src0_sel:WORD_1 src1_sel:DWORD
	v_and_b32_sdwa v73, v88, v169 dst_sel:DWORD dst_unused:UNUSED_PAD src0_sel:WORD_1 src1_sel:DWORD
	v_add3_u32 v183, v88, v73, s33
	v_add3_u32 v195, v89, v72, s33
	v_add_u32_e32 v196, 0xd000, v170
	v_perm_b32 v69, v69, v71, s50
	v_perm_b32 v68, v68, v70, s50
	v_perm_b32 v67, v67, v75, s50
	v_perm_b32 v66, v74, v66, s50
	v_perm_b32 v89, v87, v86, s50
	v_perm_b32 v88, v95, v94, s50
	v_perm_b32 v87, v93, v92, s50
	v_perm_b32 v86, v91, v90, s50
	ds_read2_b64 v[122:125], v196 offset0:8 offset1:10
	ds_read2_b64 v[82:85], v196 offset1:2
	ds_read2_b64 v[176:179], v196 offset0:4 offset1:6
	v_cndmask_b32_e64 v184, v80, 0, s[38:39]
	v_cndmask_b32_e64 v185, v81, 0, s[6:7]
	v_cndmask_b32_e64 v186, v78, 0, s[34:35]
	v_cndmask_b32_e64 v187, v79, 0, s[36:37]
	v_cndmask_b32_e64 v188, v76, 0, s[26:27]
	v_cndmask_b32_e64 v189, v77, 0, s[28:29]
	s_waitcnt lgkmcnt(1)
	v_mfma_f32_32x32x16_bf16 v[66:81], v[66:69], v[82:85], 0
	v_perm_b32 v183, v195, v183, s50
	v_perm_b32 v182, v194, v182, s50
	v_perm_b32 v181, v193, v181, s50
	v_perm_b32 v180, v192, v180, s50
	v_mfma_f32_32x32x16_bf16 v[82:97], v[86:89], v[82:85], 0
	s_nop 0
	v_mfma_f32_32x32x16_bf16 v[82:97], v[180:183], v[122:125], v[82:97]
	v_and_b32_sdwa v124, v99, v169 dst_sel:DWORD dst_unused:UNUSED_PAD src0_sel:WORD_1 src1_sel:DWORD
	v_and_b32_sdwa v125, v98, v169 dst_sel:DWORD dst_unused:UNUSED_PAD src0_sel:WORD_1 src1_sel:DWORD
	v_add3_u32 v125, v98, v125, s33
	v_add3_u32 v124, v99, v124, s33
	v_and_b32_sdwa v98, v230, v169 dst_sel:DWORD dst_unused:UNUSED_PAD src0_sel:WORD_1 src1_sel:DWORD
	v_and_b32_sdwa v99, v229, v169 dst_sel:DWORD dst_unused:UNUSED_PAD src0_sel:WORD_1 src1_sel:DWORD
	v_add3_u32 v180, v229, v99, s33
	v_add3_u32 v181, v230, v98, s33
	v_and_b32_sdwa v98, v189, v169 dst_sel:DWORD dst_unused:UNUSED_PAD src0_sel:WORD_1 src1_sel:DWORD
	v_and_b32_sdwa v99, v188, v169 dst_sel:DWORD dst_unused:UNUSED_PAD src0_sel:WORD_1 src1_sel:DWORD
	v_add3_u32 v182, v188, v99, s33
	v_add3_u32 v183, v189, v98, s33
	v_and_b32_sdwa v98, v101, v169 dst_sel:DWORD dst_unused:UNUSED_PAD src0_sel:WORD_1 src1_sel:DWORD
	v_and_b32_sdwa v99, v100, v169 dst_sel:DWORD dst_unused:UNUSED_PAD src0_sel:WORD_1 src1_sel:DWORD
	v_and_b32_sdwa v122, v191, v169 dst_sel:DWORD dst_unused:UNUSED_PAD src0_sel:WORD_1 src1_sel:DWORD
	v_and_b32_sdwa v123, v190, v169 dst_sel:DWORD dst_unused:UNUSED_PAD src0_sel:WORD_1 src1_sel:DWORD
	v_add3_u32 v188, v100, v99, s33
	v_add3_u32 v189, v101, v98, s33
	v_and_b32_sdwa v98, v228, v169 dst_sel:DWORD dst_unused:UNUSED_PAD src0_sel:WORD_1 src1_sel:DWORD
	v_and_b32_sdwa v99, v223, v169 dst_sel:DWORD dst_unused:UNUSED_PAD src0_sel:WORD_1 src1_sel:DWORD
	v_add3_u32 v123, v190, v123, s33
	v_add3_u32 v122, v191, v122, s33
	v_add3_u32 v190, v223, v99, s33
	v_add3_u32 v191, v228, v98, s33
	v_and_b32_sdwa v98, v187, v169 dst_sel:DWORD dst_unused:UNUSED_PAD src0_sel:WORD_1 src1_sel:DWORD
	v_and_b32_sdwa v99, v186, v169 dst_sel:DWORD dst_unused:UNUSED_PAD src0_sel:WORD_1 src1_sel:DWORD
	v_add3_u32 v186, v186, v99, s33
	v_add3_u32 v187, v187, v98, s33
	v_and_b32_sdwa v98, v103, v169 dst_sel:DWORD dst_unused:UNUSED_PAD src0_sel:WORD_1 src1_sel:DWORD
	v_and_b32_sdwa v99, v102, v169 dst_sel:DWORD dst_unused:UNUSED_PAD src0_sel:WORD_1 src1_sel:DWORD
	v_add3_u32 v192, v102, v99, s33
	v_add3_u32 v193, v103, v98, s33
	v_and_b32_sdwa v98, v222, v169 dst_sel:DWORD dst_unused:UNUSED_PAD src0_sel:WORD_1 src1_sel:DWORD
	v_and_b32_sdwa v99, v221, v169 dst_sel:DWORD dst_unused:UNUSED_PAD src0_sel:WORD_1 src1_sel:DWORD
	v_add3_u32 v194, v221, v99, s33
	v_add3_u32 v195, v222, v98, s33
	v_and_b32_sdwa v98, v185, v169 dst_sel:DWORD dst_unused:UNUSED_PAD src0_sel:WORD_1 src1_sel:DWORD
	v_and_b32_sdwa v99, v184, v169 dst_sel:DWORD dst_unused:UNUSED_PAD src0_sel:WORD_1 src1_sel:DWORD
	v_add3_u32 v102, v184, v99, s33
	v_add3_u32 v103, v185, v98, s33
	v_and_b32_sdwa v98, v105, v169 dst_sel:DWORD dst_unused:UNUSED_PAD src0_sel:WORD_1 src1_sel:DWORD
	v_and_b32_sdwa v99, v104, v169 dst_sel:DWORD dst_unused:UNUSED_PAD src0_sel:WORD_1 src1_sel:DWORD
	v_add3_u32 v184, v104, v99, s33
	v_add3_u32 v185, v105, v98, s33
	v_perm_b32 v105, v103, v102, s50
	v_perm_b32 v104, v187, v186, s50
	v_perm_b32 v103, v183, v182, s50
	v_perm_b32 v102, v122, v123, s50
	v_and_b32_sdwa v98, v220, v169 dst_sel:DWORD dst_unused:UNUSED_PAD src0_sel:WORD_1 src1_sel:DWORD
	v_and_b32_sdwa v99, v175, v169 dst_sel:DWORD dst_unused:UNUSED_PAD src0_sel:WORD_1 src1_sel:DWORD
	s_waitcnt lgkmcnt(0)
	v_mfma_f32_32x32x16_bf16 v[66:81], v[102:105], v[176:179], v[66:81]
	v_perm_b32 v105, v185, v184, s50
	v_perm_b32 v104, v193, v192, s50
	v_perm_b32 v103, v189, v188, s50
	v_perm_b32 v102, v124, v125, s50
	v_add3_u32 v175, v175, v99, s33
	v_add3_u32 v197, v220, v98, s33
	ds_read2_b64 v[98:101], v196 offset0:12 offset1:14
	v_mfma_f32_32x32x16_bf16 v[82:97], v[102:105], v[176:179], v[82:97]
	v_perm_b32 v105, v197, v175, s50
	v_perm_b32 v104, v195, v194, s50
	v_perm_b32 v103, v191, v190, s50
	v_perm_b32 v102, v181, v180, s50
	s_waitcnt lgkmcnt(0)
	s_nop 0
	v_mfma_f32_32x32x16_bf16 v[82:97], v[102:105], v[98:101], v[82:97]
	v_and_b32_sdwa v98, v3, v169 dst_sel:DWORD dst_unused:UNUSED_PAD src0_sel:WORD_1 src1_sel:DWORD
	v_and_b32_sdwa v99, v2, v169 dst_sel:DWORD dst_unused:UNUSED_PAD src0_sel:WORD_1 src1_sel:DWORD
	v_add3_u32 v102, v2, v99, s33
	v_add3_u32 v122, v3, v98, s33
	v_and_b32_sdwa v98, v5, v169 dst_sel:DWORD dst_unused:UNUSED_PAD src0_sel:WORD_1 src1_sel:DWORD
	v_and_b32_sdwa v99, v4, v169 dst_sel:DWORD dst_unused:UNUSED_PAD src0_sel:WORD_1 src1_sel:DWORD
	v_add3_u32 v103, v4, v99, s33
	v_add3_u32 v123, v5, v98, s33
	v_and_b32_sdwa v98, v7, v169 dst_sel:DWORD dst_unused:UNUSED_PAD src0_sel:WORD_1 src1_sel:DWORD
	v_and_b32_sdwa v99, v6, v169 dst_sel:DWORD dst_unused:UNUSED_PAD src0_sel:WORD_1 src1_sel:DWORD
	v_add3_u32 v104, v6, v99, s33
	v_add3_u32 v124, v7, v98, s33
	ds_read2_b64 v[98:101], v162 offset1:2
	v_and_b32_sdwa v105, v9, v169 dst_sel:DWORD dst_unused:UNUSED_PAD src0_sel:WORD_1 src1_sel:DWORD
	v_and_b32_sdwa v125, v8, v169 dst_sel:DWORD dst_unused:UNUSED_PAD src0_sel:WORD_1 src1_sel:DWORD
	v_add3_u32 v125, v8, v125, s33
	v_add3_u32 v105, v9, v105, s33
	v_add_u32_e32 v175, 0x2000, v162
	v_perm_b32 v105, v105, v125, s50
	v_perm_b32 v104, v124, v104, s50
	v_perm_b32 v103, v123, v103, s50
	v_perm_b32 v102, v122, v102, s50
	s_waitcnt lgkmcnt(0)
	s_nop 0
	v_mfma_f32_32x32x16_bf16 v[66:81], v[98:101], v[102:105], v[66:81]
	ds_read2_b64 v[98:101], v175 offset0:64 offset1:66
	ds_read2_b64 v[122:125], v162 offset0:4 offset1:6
	s_waitcnt lgkmcnt(1)
	v_mfma_f32_32x32x16_bf16 v[82:97], v[98:101], v[102:105], v[82:97]
	v_and_b32_sdwa v99, v10, v169 dst_sel:DWORD dst_unused:UNUSED_PAD src0_sel:WORD_1 src1_sel:DWORD
	v_and_b32_sdwa v100, v12, v169 dst_sel:DWORD dst_unused:UNUSED_PAD src0_sel:WORD_1 src1_sel:DWORD
	v_and_b32_sdwa v101, v14, v169 dst_sel:DWORD dst_unused:UNUSED_PAD src0_sel:WORD_1 src1_sel:DWORD
	v_and_b32_sdwa v98, v11, v169 dst_sel:DWORD dst_unused:UNUSED_PAD src0_sel:WORD_1 src1_sel:DWORD
	v_add3_u32 v102, v10, v99, s33
	v_and_b32_sdwa v99, v13, v169 dst_sel:DWORD dst_unused:UNUSED_PAD src0_sel:WORD_1 src1_sel:DWORD
	v_add3_u32 v103, v12, v100, s33
	v_and_b32_sdwa v100, v15, v169 dst_sel:DWORD dst_unused:UNUSED_PAD src0_sel:WORD_1 src1_sel:DWORD
	v_add3_u32 v104, v14, v101, s33
	v_and_b32_sdwa v101, v17, v169 dst_sel:DWORD dst_unused:UNUSED_PAD src0_sel:WORD_1 src1_sel:DWORD
	v_and_b32_sdwa v105, v16, v169 dst_sel:DWORD dst_unused:UNUSED_PAD src0_sel:WORD_1 src1_sel:DWORD
	v_add3_u32 v98, v11, v98, s33
	v_add3_u32 v99, v13, v99, s33
	v_add3_u32 v100, v15, v100, s33
	v_add3_u32 v105, v16, v105, s33
	v_add3_u32 v101, v17, v101, s33
	v_perm_b32 v101, v101, v105, s50
	v_perm_b32 v100, v100, v104, s50
	v_perm_b32 v99, v99, v103, s50
	v_perm_b32 v98, v98, v102, s50
	ds_read2_b64 v[102:105], v175 offset0:68 offset1:70
	s_waitcnt lgkmcnt(1)
	v_mfma_f32_32x32x16_bf16 v[66:81], v[122:125], v[98:101], v[66:81]
	s_waitcnt lgkmcnt(0)
	v_mfma_f32_32x32x16_bf16 v[82:97], v[102:105], v[98:101], v[82:97]
	v_and_b32_sdwa v98, v19, v169 dst_sel:DWORD dst_unused:UNUSED_PAD src0_sel:WORD_1 src1_sel:DWORD
	v_and_b32_sdwa v99, v18, v169 dst_sel:DWORD dst_unused:UNUSED_PAD src0_sel:WORD_1 src1_sel:DWORD
	v_add3_u32 v102, v18, v99, s33
	v_add3_u32 v122, v19, v98, s33
	v_and_b32_sdwa v98, v21, v169 dst_sel:DWORD dst_unused:UNUSED_PAD src0_sel:WORD_1 src1_sel:DWORD
	v_and_b32_sdwa v99, v20, v169 dst_sel:DWORD dst_unused:UNUSED_PAD src0_sel:WORD_1 src1_sel:DWORD
	v_add3_u32 v103, v20, v99, s33
	v_add3_u32 v123, v21, v98, s33
	v_and_b32_sdwa v98, v23, v169 dst_sel:DWORD dst_unused:UNUSED_PAD src0_sel:WORD_1 src1_sel:DWORD
	v_and_b32_sdwa v99, v22, v169 dst_sel:DWORD dst_unused:UNUSED_PAD src0_sel:WORD_1 src1_sel:DWORD
	v_add3_u32 v104, v22, v99, s33
	v_add3_u32 v124, v23, v98, s33
	ds_read2_b64 v[98:101], v162 offset0:8 offset1:10
	v_and_b32_sdwa v105, v25, v169 dst_sel:DWORD dst_unused:UNUSED_PAD src0_sel:WORD_1 src1_sel:DWORD
	v_and_b32_sdwa v125, v24, v169 dst_sel:DWORD dst_unused:UNUSED_PAD src0_sel:WORD_1 src1_sel:DWORD
	v_add3_u32 v125, v24, v125, s33
	v_add3_u32 v105, v25, v105, s33
	v_perm_b32 v105, v105, v125, s50
	v_perm_b32 v104, v124, v104, s50
	v_perm_b32 v103, v123, v103, s50
	v_perm_b32 v102, v122, v102, s50
	s_waitcnt lgkmcnt(0)
	s_nop 0
	v_mfma_f32_32x32x16_bf16 v[66:81], v[98:101], v[102:105], v[66:81]
	ds_read2_b64 v[98:101], v175 offset0:72 offset1:74
	ds_read2_b64 v[122:125], v162 offset0:12 offset1:14
	s_waitcnt lgkmcnt(1)
	v_mfma_f32_32x32x16_bf16 v[82:97], v[98:101], v[102:105], v[82:97]
	v_and_b32_sdwa v99, v26, v169 dst_sel:DWORD dst_unused:UNUSED_PAD src0_sel:WORD_1 src1_sel:DWORD
	v_and_b32_sdwa v100, v28, v169 dst_sel:DWORD dst_unused:UNUSED_PAD src0_sel:WORD_1 src1_sel:DWORD
	v_and_b32_sdwa v101, v30, v169 dst_sel:DWORD dst_unused:UNUSED_PAD src0_sel:WORD_1 src1_sel:DWORD
	v_and_b32_sdwa v98, v27, v169 dst_sel:DWORD dst_unused:UNUSED_PAD src0_sel:WORD_1 src1_sel:DWORD
	v_add3_u32 v102, v26, v99, s33
	v_and_b32_sdwa v99, v29, v169 dst_sel:DWORD dst_unused:UNUSED_PAD src0_sel:WORD_1 src1_sel:DWORD
	v_add3_u32 v103, v28, v100, s33
	v_and_b32_sdwa v100, v31, v169 dst_sel:DWORD dst_unused:UNUSED_PAD src0_sel:WORD_1 src1_sel:DWORD
	v_add3_u32 v104, v30, v101, s33
	v_and_b32_sdwa v101, v33, v169 dst_sel:DWORD dst_unused:UNUSED_PAD src0_sel:WORD_1 src1_sel:DWORD
	v_and_b32_sdwa v105, v32, v169 dst_sel:DWORD dst_unused:UNUSED_PAD src0_sel:WORD_1 src1_sel:DWORD
	v_add3_u32 v98, v27, v98, s33
	v_add3_u32 v99, v29, v99, s33
	v_add3_u32 v100, v31, v100, s33
	v_add3_u32 v105, v32, v105, s33
	v_add3_u32 v101, v33, v101, s33
	v_perm_b32 v101, v101, v105, s50
	v_perm_b32 v100, v100, v104, s50
	v_perm_b32 v99, v99, v103, s50
	v_perm_b32 v98, v98, v102, s50
	ds_read2_b64 v[102:105], v175 offset0:76 offset1:78
	s_waitcnt lgkmcnt(1)
	v_mfma_f32_32x32x16_bf16 v[66:81], v[122:125], v[98:101], v[66:81]
	s_waitcnt lgkmcnt(0)
	v_mfma_f32_32x32x16_bf16 v[82:97], v[102:105], v[98:101], v[82:97]
	v_and_b32_sdwa v98, v35, v169 dst_sel:DWORD dst_unused:UNUSED_PAD src0_sel:WORD_1 src1_sel:DWORD
	v_and_b32_sdwa v99, v34, v169 dst_sel:DWORD dst_unused:UNUSED_PAD src0_sel:WORD_1 src1_sel:DWORD
	v_add3_u32 v102, v34, v99, s33
	v_add3_u32 v122, v35, v98, s33
	v_and_b32_sdwa v98, v37, v169 dst_sel:DWORD dst_unused:UNUSED_PAD src0_sel:WORD_1 src1_sel:DWORD
	v_and_b32_sdwa v99, v36, v169 dst_sel:DWORD dst_unused:UNUSED_PAD src0_sel:WORD_1 src1_sel:DWORD
	v_add3_u32 v103, v36, v99, s33
	v_add3_u32 v123, v37, v98, s33
	v_and_b32_sdwa v98, v39, v169 dst_sel:DWORD dst_unused:UNUSED_PAD src0_sel:WORD_1 src1_sel:DWORD
	v_and_b32_sdwa v99, v38, v169 dst_sel:DWORD dst_unused:UNUSED_PAD src0_sel:WORD_1 src1_sel:DWORD
	v_add3_u32 v104, v38, v99, s33
	v_add3_u32 v124, v39, v98, s33
	ds_read2_b64 v[98:101], v162 offset0:16 offset1:18
	v_and_b32_sdwa v105, v41, v169 dst_sel:DWORD dst_unused:UNUSED_PAD src0_sel:WORD_1 src1_sel:DWORD
	v_and_b32_sdwa v125, v40, v169 dst_sel:DWORD dst_unused:UNUSED_PAD src0_sel:WORD_1 src1_sel:DWORD
	v_add3_u32 v125, v40, v125, s33
	v_add3_u32 v105, v41, v105, s33
	v_perm_b32 v105, v105, v125, s50
	v_perm_b32 v104, v124, v104, s50
	v_perm_b32 v103, v123, v103, s50
	v_perm_b32 v102, v122, v102, s50
	s_waitcnt lgkmcnt(0)
	s_nop 0
	v_mfma_f32_32x32x16_bf16 v[66:81], v[98:101], v[102:105], v[66:81]
	ds_read2_b64 v[98:101], v175 offset0:80 offset1:82
	ds_read2_b64 v[122:125], v162 offset0:20 offset1:22
	s_waitcnt lgkmcnt(1)
	v_mfma_f32_32x32x16_bf16 v[82:97], v[98:101], v[102:105], v[82:97]
	v_and_b32_sdwa v99, v42, v169 dst_sel:DWORD dst_unused:UNUSED_PAD src0_sel:WORD_1 src1_sel:DWORD
	v_and_b32_sdwa v100, v44, v169 dst_sel:DWORD dst_unused:UNUSED_PAD src0_sel:WORD_1 src1_sel:DWORD
	v_and_b32_sdwa v101, v46, v169 dst_sel:DWORD dst_unused:UNUSED_PAD src0_sel:WORD_1 src1_sel:DWORD
	v_and_b32_sdwa v98, v43, v169 dst_sel:DWORD dst_unused:UNUSED_PAD src0_sel:WORD_1 src1_sel:DWORD
	v_add3_u32 v102, v42, v99, s33
	v_and_b32_sdwa v99, v45, v169 dst_sel:DWORD dst_unused:UNUSED_PAD src0_sel:WORD_1 src1_sel:DWORD
	v_add3_u32 v103, v44, v100, s33
	v_and_b32_sdwa v100, v47, v169 dst_sel:DWORD dst_unused:UNUSED_PAD src0_sel:WORD_1 src1_sel:DWORD
	v_add3_u32 v104, v46, v101, s33
	v_and_b32_sdwa v101, v49, v169 dst_sel:DWORD dst_unused:UNUSED_PAD src0_sel:WORD_1 src1_sel:DWORD
	v_and_b32_sdwa v105, v48, v169 dst_sel:DWORD dst_unused:UNUSED_PAD src0_sel:WORD_1 src1_sel:DWORD
	v_add3_u32 v98, v43, v98, s33
	v_add3_u32 v99, v45, v99, s33
	v_add3_u32 v100, v47, v100, s33
	v_add3_u32 v105, v48, v105, s33
	v_add3_u32 v101, v49, v101, s33
	v_perm_b32 v101, v101, v105, s50
	v_perm_b32 v100, v100, v104, s50
	v_perm_b32 v99, v99, v103, s50
	v_perm_b32 v98, v98, v102, s50
	ds_read2_b64 v[102:105], v175 offset0:84 offset1:86
	s_waitcnt lgkmcnt(1)
	v_mfma_f32_32x32x16_bf16 v[66:81], v[122:125], v[98:101], v[66:81]
	s_waitcnt lgkmcnt(0)
	v_mfma_f32_32x32x16_bf16 v[82:97], v[102:105], v[98:101], v[82:97]
	v_and_b32_sdwa v98, v51, v169 dst_sel:DWORD dst_unused:UNUSED_PAD src0_sel:WORD_1 src1_sel:DWORD
	v_and_b32_sdwa v99, v50, v169 dst_sel:DWORD dst_unused:UNUSED_PAD src0_sel:WORD_1 src1_sel:DWORD
	v_add3_u32 v102, v50, v99, s33
	v_add3_u32 v122, v51, v98, s33
	v_and_b32_sdwa v98, v53, v169 dst_sel:DWORD dst_unused:UNUSED_PAD src0_sel:WORD_1 src1_sel:DWORD
	v_and_b32_sdwa v99, v52, v169 dst_sel:DWORD dst_unused:UNUSED_PAD src0_sel:WORD_1 src1_sel:DWORD
	v_add3_u32 v103, v52, v99, s33
	v_add3_u32 v123, v53, v98, s33
	v_and_b32_sdwa v98, v55, v169 dst_sel:DWORD dst_unused:UNUSED_PAD src0_sel:WORD_1 src1_sel:DWORD
	v_and_b32_sdwa v99, v54, v169 dst_sel:DWORD dst_unused:UNUSED_PAD src0_sel:WORD_1 src1_sel:DWORD
	v_add3_u32 v104, v54, v99, s33
	v_add3_u32 v124, v55, v98, s33
	ds_read2_b64 v[98:101], v162 offset0:24 offset1:26
	v_and_b32_sdwa v105, v57, v169 dst_sel:DWORD dst_unused:UNUSED_PAD src0_sel:WORD_1 src1_sel:DWORD
	v_and_b32_sdwa v125, v56, v169 dst_sel:DWORD dst_unused:UNUSED_PAD src0_sel:WORD_1 src1_sel:DWORD
	v_add3_u32 v125, v56, v125, s33
	v_add3_u32 v105, v57, v105, s33
	v_perm_b32 v105, v105, v125, s50
	v_perm_b32 v104, v124, v104, s50
	v_perm_b32 v103, v123, v103, s50
	v_perm_b32 v102, v122, v102, s50
	s_waitcnt lgkmcnt(0)
	s_nop 0
	v_mfma_f32_32x32x16_bf16 v[66:81], v[98:101], v[102:105], v[66:81]
	ds_read2_b64 v[122:125], v175 offset0:88 offset1:90
	ds_read2_b64 v[98:101], v162 offset0:28 offset1:30
	s_waitcnt lgkmcnt(1)
	v_mfma_f32_32x32x16_bf16 v[82:97], v[122:125], v[102:105], v[82:97]
	v_and_b32_sdwa v102, v59, v169 dst_sel:DWORD dst_unused:UNUSED_PAD src0_sel:WORD_1 src1_sel:DWORD
	v_and_b32_sdwa v103, v58, v169 dst_sel:DWORD dst_unused:UNUSED_PAD src0_sel:WORD_1 src1_sel:DWORD
	v_add3_u32 v122, v58, v103, s33
	v_add3_u32 v176, v59, v102, s33
	v_and_b32_sdwa v102, v61, v169 dst_sel:DWORD dst_unused:UNUSED_PAD src0_sel:WORD_1 src1_sel:DWORD
	v_and_b32_sdwa v103, v60, v169 dst_sel:DWORD dst_unused:UNUSED_PAD src0_sel:WORD_1 src1_sel:DWORD
	v_add3_u32 v123, v60, v103, s33
	v_add3_u32 v177, v61, v102, s33
	v_and_b32_sdwa v102, v63, v169 dst_sel:DWORD dst_unused:UNUSED_PAD src0_sel:WORD_1 src1_sel:DWORD
	v_and_b32_sdwa v103, v62, v169 dst_sel:DWORD dst_unused:UNUSED_PAD src0_sel:WORD_1 src1_sel:DWORD
	v_add3_u32 v124, v62, v103, s33
	v_add3_u32 v178, v63, v102, s33
	v_and_b32_sdwa v102, v65, v169 dst_sel:DWORD dst_unused:UNUSED_PAD src0_sel:WORD_1 src1_sel:DWORD
	v_and_b32_sdwa v103, v64, v169 dst_sel:DWORD dst_unused:UNUSED_PAD src0_sel:WORD_1 src1_sel:DWORD
	v_add3_u32 v125, v64, v103, s33
	v_add3_u32 v179, v65, v102, s33
	ds_read2_b64 v[102:105], v175 offset0:92 offset1:94
	v_perm_b32 v125, v179, v125, s50
	v_perm_b32 v124, v178, v124, s50
	v_perm_b32 v123, v177, v123, s50
	v_perm_b32 v122, v176, v122, s50
	ds_read_b128 v[176:179], v163 offset:34816
	ds_read_b128 v[180:183], v163 offset:34848
	ds_read_b128 v[184:187], v174 offset:53248
	ds_read_b128 v[188:191], v174 offset:53280
	s_waitcnt lgkmcnt(1)
	v_mfma_f32_32x32x16_bf16 v[2:17], v[176:179], v[184:187], v[2:17]
	s_waitcnt lgkmcnt(0)
	v_mfma_f32_32x32x16_bf16 v[2:17], v[180:183], v[188:191], v[2:17]
	ds_read_b128 v[176:179], v163 offset:34880
	ds_read_b128 v[180:183], v174 offset:53312
	s_waitcnt lgkmcnt(0)
	v_mfma_f32_32x32x16_bf16 v[2:17], v[176:179], v[180:183], v[2:17]
	ds_read_b128 v[176:179], v163 offset:34912
	ds_read_b128 v[180:183], v174 offset:53344
	s_waitcnt lgkmcnt(0)
	v_mfma_f32_32x32x16_bf16 v[2:17], v[176:179], v[180:183], v[2:17]
	ds_read_b128 v[176:179], v155
	ds_read_b128 v[180:183], v155 offset:32
	s_waitcnt lgkmcnt(1)
	s_nop 8
	v_pk_mul_f32 v[2:3], v[176:177], v[2:3]
	v_pk_mul_f32 v[4:5], v[4:5], v[178:179]
	ds_read_b128 v[176:179], v155 offset:64
	s_waitcnt lgkmcnt(1)
	v_pk_mul_f32 v[6:7], v[6:7], v[180:181]
	v_pk_mul_f32 v[8:9], v[8:9], v[182:183]
	s_waitcnt lgkmcnt(0)
	v_pk_mul_f32 v[10:11], v[10:11], v[176:177]
	v_pk_mul_f32 v[12:13], v[12:13], v[178:179]
	ds_read_b128 v[176:179], v155 offset:96
	s_waitcnt lgkmcnt(0)
	v_pk_mul_f32 v[14:15], v[14:15], v[176:177]
	v_pk_mul_f32 v[16:17], v[16:17], v[178:179]
	ds_read_b128 v[176:179], v163 offset:39424
	ds_read_b128 v[180:183], v163 offset:39456
	ds_read_b128 v[184:187], v174 offset:53248
	ds_read_b128 v[188:191], v174 offset:53280
	s_waitcnt lgkmcnt(1)
	v_mfma_f32_32x32x16_bf16 v[18:33], v[176:179], v[184:187], v[18:33]
	s_waitcnt lgkmcnt(0)
	v_mfma_f32_32x32x16_bf16 v[18:33], v[180:183], v[188:191], v[18:33]
	ds_read_b128 v[176:179], v163 offset:39488
	ds_read_b128 v[180:183], v174 offset:53312
	s_waitcnt lgkmcnt(0)
	v_mfma_f32_32x32x16_bf16 v[18:33], v[176:179], v[180:183], v[18:33]
	ds_read_b128 v[176:179], v163 offset:39520
	ds_read_b128 v[180:183], v174 offset:53344
	s_waitcnt lgkmcnt(0)
	v_mfma_f32_32x32x16_bf16 v[18:33], v[176:179], v[180:183], v[18:33]
	ds_read_b128 v[176:179], v155 offset:128
	ds_read_b128 v[180:183], v155 offset:160
	s_waitcnt lgkmcnt(1)
	s_nop 8
	v_pk_mul_f32 v[18:19], v[176:177], v[18:19]
	v_pk_mul_f32 v[20:21], v[20:21], v[178:179]
	ds_read_b128 v[176:179], v155 offset:192
	s_waitcnt lgkmcnt(1)
	v_pk_mul_f32 v[22:23], v[22:23], v[180:181]
	v_pk_mul_f32 v[24:25], v[24:25], v[182:183]
	s_waitcnt lgkmcnt(0)
	v_pk_mul_f32 v[26:27], v[26:27], v[176:177]
	v_pk_mul_f32 v[28:29], v[28:29], v[178:179]
	ds_read_b128 v[176:179], v155 offset:224
	s_waitcnt lgkmcnt(0)
	v_pk_mul_f32 v[30:31], v[30:31], v[176:177]
	v_pk_mul_f32 v[32:33], v[32:33], v[178:179]
	ds_read_b128 v[176:179], v163 offset:44032
	ds_read_b128 v[180:183], v163 offset:44064
	ds_read_b128 v[184:187], v174 offset:53248
	ds_read_b128 v[188:191], v174 offset:53280
	s_waitcnt lgkmcnt(1)
	v_mfma_f32_32x32x16_bf16 v[34:49], v[176:179], v[184:187], v[34:49]
	s_waitcnt lgkmcnt(0)
	v_mfma_f32_32x32x16_bf16 v[34:49], v[180:183], v[188:191], v[34:49]
	ds_read_b128 v[176:179], v163 offset:44096
	ds_read_b128 v[180:183], v174 offset:53312
	s_waitcnt lgkmcnt(0)
	v_mfma_f32_32x32x16_bf16 v[34:49], v[176:179], v[180:183], v[34:49]
	ds_read_b128 v[176:179], v163 offset:44128
	ds_read_b128 v[180:183], v174 offset:53344
	s_waitcnt lgkmcnt(0)
	v_mfma_f32_32x32x16_bf16 v[34:49], v[176:179], v[180:183], v[34:49]
	ds_read_b128 v[176:179], v155 offset:256
	ds_read_b128 v[180:183], v155 offset:288
	s_waitcnt lgkmcnt(1)
	s_nop 8
	v_pk_mul_f32 v[34:35], v[176:177], v[34:35]
	v_pk_mul_f32 v[36:37], v[36:37], v[178:179]
	ds_read_b128 v[176:179], v155 offset:320
	s_waitcnt lgkmcnt(1)
	v_pk_mul_f32 v[38:39], v[38:39], v[180:181]
	v_pk_mul_f32 v[40:41], v[40:41], v[182:183]
	s_waitcnt lgkmcnt(0)
	v_pk_mul_f32 v[42:43], v[42:43], v[176:177]
	v_pk_mul_f32 v[44:45], v[44:45], v[178:179]
	ds_read_b128 v[176:179], v155 offset:352
	s_waitcnt lgkmcnt(0)
	v_pk_mul_f32 v[46:47], v[46:47], v[176:177]
	v_pk_mul_f32 v[48:49], v[48:49], v[178:179]
	ds_read_b128 v[176:179], v163 offset:48640
	ds_read_b128 v[180:183], v163 offset:48672
	ds_read_b128 v[184:187], v174 offset:53248
	ds_read_b128 v[188:191], v174 offset:53280
	s_waitcnt lgkmcnt(1)
	v_mfma_f32_32x32x16_bf16 v[50:65], v[176:179], v[184:187], v[50:65]
	s_waitcnt lgkmcnt(0)
	v_mfma_f32_32x32x16_bf16 v[50:65], v[180:183], v[188:191], v[50:65]
	ds_read_b128 v[176:179], v163 offset:48704
	ds_read_b128 v[180:183], v174 offset:53312
	s_waitcnt lgkmcnt(0)
	v_mfma_f32_32x32x16_bf16 v[50:65], v[176:179], v[180:183], v[50:65]
	ds_read_b128 v[176:179], v163 offset:48736
	ds_read_b128 v[180:183], v174 offset:53344
	s_waitcnt lgkmcnt(0)
	v_mfma_f32_32x32x16_bf16 v[50:65], v[176:179], v[180:183], v[50:65]
	ds_read_b128 v[176:179], v155 offset:384
	ds_read_b128 v[180:183], v155 offset:416
	s_waitcnt lgkmcnt(1)
	s_nop 8
	v_pk_mul_f32 v[50:51], v[176:177], v[50:51]
	v_pk_mul_f32 v[52:53], v[52:53], v[178:179]
	ds_read_b128 v[176:179], v155 offset:448
	s_waitcnt lgkmcnt(1)
	v_pk_mul_f32 v[54:55], v[54:55], v[180:181]
	v_pk_mul_f32 v[56:57], v[56:57], v[182:183]
	s_waitcnt lgkmcnt(0)
	v_pk_mul_f32 v[58:59], v[58:59], v[176:177]
	v_pk_mul_f32 v[60:61], v[60:61], v[178:179]
	ds_read_b128 v[176:179], v155 offset:480
	s_waitcnt lgkmcnt(0)
	v_pk_mul_f32 v[62:63], v[62:63], v[176:177]
	v_pk_mul_f32 v[64:65], v[64:65], v[178:179]
	v_mfma_f32_32x32x16_bf16 v[66:81], v[98:101], v[122:125], v[66:81]
	s_barrier
	v_add_u32_e32 v98, 0x4200, v171
	s_waitcnt vmcnt(7)
	v_and_b32_e32 v177, 0xffff0000, v121
	v_and_b32_e32 v176, 0xffff0000, v120
	s_mov_b32 s42, 0x800000
	v_mfma_f32_32x32x16_bf16 v[82:97], v[102:105], v[122:125], v[82:97]
	s_nop 4
	ds_write2_b32 v171, v66, v67 offset1:132
	v_add_u32_e32 v66, 0x400, v171
	ds_write2_b32 v66, v68, v69 offset0:8 offset1:140
	v_add_u32_e32 v66, 0x4600, v171
	v_lshlrev_b32_e32 v105, 16, v119
	v_lshlrev_b32_e32 v104, 16, v118
	v_and_b32_e32 v123, 0xffff0000, v119
	ds_write2_b32 v66, v84, v85 offset0:8 offset1:140
	v_add_u32_e32 v66, 0x1000, v171
	ds_write2_b32 v66, v70, v71 offset0:32 offset1:164
	v_add_u32_e32 v66, 0x5200, v171
	ds_write2_b32 v66, v86, v87 offset0:32 offset1:164
	v_add_u32_e32 v66, 0x1400, v171
	ds_write2_b32 v66, v72, v73 offset0:40 offset1:172
	v_add_u32_e32 v66, 0x5600, v171
	ds_write2_b32 v66, v88, v89 offset0:40 offset1:172
	v_add_u32_e32 v66, 0x2000, v171
	ds_write2_b32 v66, v74, v75 offset0:64 offset1:196
	v_add_u32_e32 v66, 0x6200, v171
	ds_write2_b32 v66, v90, v91 offset0:64 offset1:196
	v_add_u32_e32 v66, 0x2400, v171
	ds_write2_b32 v66, v76, v77 offset0:72 offset1:204
	v_add_u32_e32 v66, 0x6600, v171
	ds_write2_b32 v66, v92, v93 offset0:72 offset1:204
	v_add_u32_e32 v66, 0x3000, v171
	ds_write2_b32 v66, v78, v79 offset0:96 offset1:228
	v_add_u32_e32 v66, 0x7200, v171
	ds_write2_b32 v66, v94, v95 offset0:96 offset1:228
	v_add_u32_e32 v66, 0x3400, v171
	ds_write2_b32 v66, v80, v81 offset0:104 offset1:236
	v_add_u32_e32 v66, 0x7600, v171
	ds_write2_b32 v98, v82, v83 offset1:132
	ds_write2_b32 v66, v96, v97 offset0:104 offset1:236
	s_waitcnt lgkmcnt(0)
	s_barrier
	global_load_dwordx4 v[92:95], v[128:129], off
	global_load_dwordx4 v[96:99], v[128:129], off offset:16
	ds_read_b128 v[100:103], v157
	v_and_b32_e32 v122, 0xffff0000, v118
	v_lshlrev_b32_e32 v125, 16, v121
	v_lshlrev_b32_e32 v124, 16, v120
	ds_read_b128 v[118:121], v157 offset:16
	ds_read_b128 v[78:81], v157 offset:32
	ds_read_b128 v[74:77], v157 offset:48
	s_waitcnt lgkmcnt(3)
	v_pk_mul_f32 v[182:183], v[100:101], v[100:101]
	v_mov_b32_e32 v178, v100
	v_pk_mul_f32 v[180:181], v[102:103], v[102:103]
	v_add_f32_e32 v100, v182, v183
	v_add_f32_e32 v100, v100, v180
	s_waitcnt lgkmcnt(2)
	v_pk_mul_f32 v[186:187], v[118:119], v[118:119]
	v_add_f32_e32 v100, v100, v181
	v_add_f32_e32 v100, v100, v186
	v_pk_mul_f32 v[184:185], v[120:121], v[120:121]
	v_add_f32_e32 v100, v100, v187
	v_add_f32_e32 v100, v100, v184
	s_waitcnt lgkmcnt(1)
	v_pk_mul_f32 v[190:191], v[78:79], v[78:79]
	v_add_f32_e32 v100, v100, v185
	v_add_f32_e32 v100, v100, v190
	v_pk_mul_f32 v[188:189], v[80:81], v[80:81]
	v_add_f32_e32 v100, v100, v191
	ds_read_b128 v[86:89], v157 offset:64
	ds_read_b128 v[82:85], v157 offset:80
	v_add_f32_e32 v100, v100, v188
	s_waitcnt lgkmcnt(2)
	v_pk_mul_f32 v[194:195], v[74:75], v[74:75]
	v_add_f32_e32 v100, v100, v189
	v_add_f32_e32 v100, v100, v194
	v_pk_mul_f32 v[192:193], v[76:77], v[76:77]
	v_add_f32_e32 v100, v100, v195
	v_add_f32_e32 v100, v100, v192
	s_waitcnt lgkmcnt(1)
	v_pk_mul_f32 v[198:199], v[86:87], v[86:87]
	v_add_f32_e32 v100, v100, v193
	v_add_f32_e32 v100, v100, v198
	v_pk_mul_f32 v[196:197], v[88:89], v[88:89]
	v_add_f32_e32 v100, v100, v199
	ds_read_b128 v[66:69], v157 offset:96
	ds_read_b128 v[70:73], v157 offset:112
	v_add_f32_e32 v100, v100, v196
	s_waitcnt lgkmcnt(2)
	v_pk_mul_f32 v[202:203], v[82:83], v[82:83]
	v_add_f32_e32 v100, v100, v197
	v_add_f32_e32 v100, v100, v202
	v_pk_mul_f32 v[200:201], v[84:85], v[84:85]
	v_add_f32_e32 v100, v100, v203
	v_add_f32_e32 v100, v100, v200
	s_waitcnt lgkmcnt(1)
	v_pk_mul_f32 v[204:205], v[66:67], v[66:67]
	v_add_f32_e32 v100, v100, v201
	v_add_f32_e32 v100, v100, v204
	v_pk_mul_f32 v[206:207], v[68:69], v[68:69]
	v_add_f32_e32 v100, v100, v205
	v_add_f32_e32 v100, v100, v206
	s_waitcnt lgkmcnt(0)
	v_pk_mul_f32 v[208:209], v[70:71], v[70:71]
	v_add_f32_e32 v100, v100, v207
	v_add_f32_e32 v100, v100, v208
	v_pk_mul_f32 v[210:211], v[72:73], v[72:73]
	v_add_f32_e32 v100, v100, v209
	v_add_f32_e32 v100, v100, v210
	v_add_f32_e32 v175, v100, v211
	ds_bpermute_b32 v180, v172, v175
	v_mov_b32_e32 v179, v102
	v_mov_b32_e32 v102, v101
	v_mov_b32_e32 v181, v120
	v_mov_b32_e32 v120, v119
	v_lshl_add_u64 v[90:91], s[82:83], 0, v[144:145]
	s_add_i32 s44, s44, -1
	v_lshl_add_u64 v[138:139], v[138:139], 0, s[62:63]
	v_lshl_add_u64 v[140:141], v[140:141], 0, s[90:91]
	v_lshl_add_u64 v[142:143], v[142:143], 0, s[62:63]
	s_cmp_eq_u32 s44, 0
	v_lshl_add_u64 v[144:145], v[144:145], 0, s[90:91]
	s_waitcnt vmcnt(1)
	v_mov_b32_e32 v100, v92
	s_waitcnt lgkmcnt(0)
	v_add_f32_e32 v92, v175, v180
	ds_bpermute_b32 v175, v173, v92
	v_mov_b32_e32 v101, v94
	v_mov_b32_e32 v94, v93
	v_mov_b32_e32 v180, v118
	s_waitcnt vmcnt(0)
	v_mov_b32_e32 v118, v96
	s_waitcnt lgkmcnt(0)
	v_add_f32_e32 v92, v92, v175
	v_fmamk_f32 v92, v92, 0x3c000000, v164
	v_mul_f32_e32 v93, 0x4b800000, v92
	v_cmp_gt_f32_e32 vcc, s42, v92
	v_mov_b32_e32 v119, v98
	v_mov_b32_e32 v98, v97
	v_cndmask_b32_e32 v92, v92, v93, vcc
	v_rsq_f32_e32 v92, v92
	s_nop 0
	v_mul_f32_e32 v93, 0x45800000, v92
	v_cndmask_b32_e32 v92, v92, v93, vcc
	v_pk_mul_f32 v[96:97], v[178:179], v[92:93] op_sel_hi:[1,0]
	s_nop 0
	v_pk_mul_f32 v[96:97], v[100:101], v[96:97]
	v_pk_mul_f32 v[100:101], v[102:103], v[92:93] op_sel_hi:[1,0]
	v_pk_mul_f32 v[96:97], v[96:97], v[104:105]
	v_pk_mul_f32 v[94:95], v[94:95], v[100:101]
	v_and_b32_sdwa v100, v96, v169 dst_sel:DWORD dst_unused:UNUSED_PAD src0_sel:WORD_1 src1_sel:DWORD
	v_pk_mul_f32 v[94:95], v[94:95], v[122:123]
	v_add3_u32 v96, v96, v100, s33
	v_and_b32_sdwa v100, v94, v169 dst_sel:DWORD dst_unused:UNUSED_PAD src0_sel:WORD_1 src1_sel:DWORD
	v_and_b32_sdwa v93, v97, v169 dst_sel:DWORD dst_unused:UNUSED_PAD src0_sel:WORD_1 src1_sel:DWORD
	v_add3_u32 v94, v94, v100, s33
	v_add3_u32 v93, v97, v93, s33
	v_and_b32_sdwa v97, v95, v169 dst_sel:DWORD dst_unused:UNUSED_PAD src0_sel:WORD_1 src1_sel:DWORD
	v_and_b32_e32 v94, 0xffff0000, v94
	v_add3_u32 v95, v95, v97, s33
	v_or_b32_sdwa v94, v94, v96 dst_sel:DWORD dst_unused:UNUSED_PAD src0_sel:DWORD src1_sel:WORD_1
	v_pk_mul_f32 v[96:97], v[180:181], v[92:93] op_sel_hi:[1,0]
	v_pk_mul_f32 v[100:101], v[120:121], v[92:93] op_sel_hi:[1,0]
	v_pk_mul_f32 v[96:97], v[118:119], v[96:97]
	v_and_b32_e32 v95, 0xffff0000, v95
	v_pk_mul_f32 v[96:97], v[96:97], v[124:125]
	v_pk_mul_f32 v[98:99], v[98:99], v[100:101]
	v_or_b32_sdwa v95, v95, v93 dst_sel:DWORD dst_unused:UNUSED_PAD src0_sel:DWORD src1_sel:WORD_1
	v_pk_mul_f32 v[98:99], v[98:99], v[176:177]
	v_and_b32_sdwa v93, v97, v169 dst_sel:DWORD dst_unused:UNUSED_PAD src0_sel:WORD_1 src1_sel:DWORD
	v_and_b32_sdwa v100, v96, v169 dst_sel:DWORD dst_unused:UNUSED_PAD src0_sel:WORD_1 src1_sel:DWORD
	v_add3_u32 v96, v96, v100, s33
	v_add3_u32 v93, v97, v93, s33
	v_and_b32_sdwa v97, v99, v169 dst_sel:DWORD dst_unused:UNUSED_PAD src0_sel:WORD_1 src1_sel:DWORD
	v_and_b32_sdwa v100, v98, v169 dst_sel:DWORD dst_unused:UNUSED_PAD src0_sel:WORD_1 src1_sel:DWORD
	v_add3_u32 v97, v99, v97, s33
	v_add3_u32 v98, v98, v100, s33
	v_and_b32_e32 v97, 0xffff0000, v97
	v_and_b32_e32 v98, 0xffff0000, v98
	v_or_b32_sdwa v97, v97, v93 dst_sel:DWORD dst_unused:UNUSED_PAD src0_sel:DWORD src1_sel:WORD_1
	v_or_b32_sdwa v96, v98, v96 dst_sel:DWORD dst_unused:UNUSED_PAD src0_sel:DWORD src1_sel:WORD_1
	global_store_dwordx4 v[90:91], v[94:97], off offset:-32
	global_load_dwordx4 v[94:97], v[128:129], off offset:32
	s_nop 0
	global_load_dwordx4 v[98:101], v[128:129], off offset:48
	v_mov_b32_e32 v118, v78
	v_mov_b32_e32 v119, v80
	v_mov_b32_e32 v80, v79
	v_mov_b32_e32 v78, v74
	v_mov_b32_e32 v79, v76
	v_mov_b32_e32 v76, v75
	v_pk_mul_f32 v[74:75], v[118:119], v[92:93] op_sel_hi:[1,0]
	v_lshlrev_b32_e32 v103, 16, v115
	v_lshlrev_b32_e32 v102, 16, v114
	v_pk_mul_f32 v[80:81], v[80:81], v[92:93] op_sel_hi:[1,0]
	v_and_b32_e32 v105, 0xffff0000, v115
	v_and_b32_e32 v104, 0xffff0000, v114
	v_lshlrev_b32_e32 v115, 16, v117
	v_lshlrev_b32_e32 v114, 16, v116
	v_and_b32_e32 v117, 0xffff0000, v117
	v_and_b32_e32 v116, 0xffff0000, v116
	s_waitcnt vmcnt(1)
	v_mov_b32_e32 v118, v94
	v_mov_b32_e32 v119, v96
	v_pk_mul_f32 v[74:75], v[74:75], v[118:119]
	v_mov_b32_e32 v96, v95
	v_pk_mul_f32 v[74:75], v[74:75], v[102:103]
	v_pk_mul_f32 v[80:81], v[80:81], v[96:97]
	v_and_b32_sdwa v93, v75, v169 dst_sel:DWORD dst_unused:UNUSED_PAD src0_sel:WORD_1 src1_sel:DWORD
	v_pk_mul_f32 v[80:81], v[80:81], v[104:105]
	v_and_b32_sdwa v94, v74, v169 dst_sel:DWORD dst_unused:UNUSED_PAD src0_sel:WORD_1 src1_sel:DWORD
	v_add3_u32 v74, v74, v94, s33
	v_add3_u32 v75, v75, v93, s33
	v_and_b32_sdwa v93, v81, v169 dst_sel:DWORD dst_unused:UNUSED_PAD src0_sel:WORD_1 src1_sel:DWORD
	v_and_b32_sdwa v94, v80, v169 dst_sel:DWORD dst_unused:UNUSED_PAD src0_sel:WORD_1 src1_sel:DWORD
	v_add3_u32 v81, v81, v93, s33
	v_add3_u32 v80, v80, v94, s33
	v_and_b32_e32 v81, 0xffff0000, v81
	v_and_b32_e32 v80, 0xffff0000, v80
	v_or_b32_sdwa v75, v81, v75 dst_sel:DWORD dst_unused:UNUSED_PAD src0_sel:DWORD src1_sel:WORD_1
	v_or_b32_sdwa v74, v80, v74 dst_sel:DWORD dst_unused:UNUSED_PAD src0_sel:DWORD src1_sel:WORD_1
	v_pk_mul_f32 v[78:79], v[78:79], v[92:93] op_sel_hi:[1,0]
	s_waitcnt vmcnt(0)
	v_mov_b32_e32 v80, v98
	v_mov_b32_e32 v81, v100
	v_pk_mul_f32 v[78:79], v[78:79], v[80:81]
	v_pk_mul_f32 v[76:77], v[76:77], v[92:93] op_sel_hi:[1,0]
	v_mov_b32_e32 v100, v99
	v_pk_mul_f32 v[78:79], v[78:79], v[114:115]
	v_pk_mul_f32 v[76:77], v[76:77], v[100:101]
	v_and_b32_sdwa v80, v79, v169 dst_sel:DWORD dst_unused:UNUSED_PAD src0_sel:WORD_1 src1_sel:DWORD
	v_pk_mul_f32 v[76:77], v[76:77], v[116:117]
	v_and_b32_sdwa v81, v78, v169 dst_sel:DWORD dst_unused:UNUSED_PAD src0_sel:WORD_1 src1_sel:DWORD
	v_add3_u32 v78, v78, v81, s33
	v_add3_u32 v79, v79, v80, s33
	v_and_b32_sdwa v80, v77, v169 dst_sel:DWORD dst_unused:UNUSED_PAD src0_sel:WORD_1 src1_sel:DWORD
	v_and_b32_sdwa v81, v76, v169 dst_sel:DWORD dst_unused:UNUSED_PAD src0_sel:WORD_1 src1_sel:DWORD
	v_add3_u32 v77, v77, v80, s33
	v_add3_u32 v76, v76, v81, s33
	v_and_b32_e32 v77, 0xffff0000, v77
	v_and_b32_e32 v76, 0xffff0000, v76
	v_or_b32_sdwa v77, v77, v79 dst_sel:DWORD dst_unused:UNUSED_PAD src0_sel:DWORD src1_sel:WORD_1
	v_or_b32_sdwa v76, v76, v78 dst_sel:DWORD dst_unused:UNUSED_PAD src0_sel:DWORD src1_sel:WORD_1
	global_store_dwordx4 v[90:91], v[74:77], off offset:-16
	global_load_dwordx4 v[74:77], v[128:129], off offset:64
	s_nop 0
	global_load_dwordx4 v[78:81], v[128:129], off offset:80
	v_mov_b32_e32 v102, v86
	v_mov_b32_e32 v103, v88
	v_mov_b32_e32 v88, v87
	v_mov_b32_e32 v86, v82
	v_mov_b32_e32 v87, v84
	v_mov_b32_e32 v84, v83
	v_pk_mul_f32 v[82:83], v[102:103], v[92:93] op_sel_hi:[1,0]
	v_pk_mul_f32 v[88:89], v[88:89], v[92:93] op_sel_hi:[1,0]
	v_lshlrev_b32_e32 v95, 16, v111
	v_lshlrev_b32_e32 v94, 16, v110
	v_and_b32_e32 v97, 0xffff0000, v111
	v_and_b32_e32 v96, 0xffff0000, v110
	v_pk_mul_f32 v[86:87], v[86:87], v[92:93] op_sel_hi:[1,0]
	v_lshlrev_b32_e32 v99, 16, v113
	v_lshlrev_b32_e32 v98, 16, v112
	v_pk_mul_f32 v[84:85], v[84:85], v[92:93] op_sel_hi:[1,0]
	v_and_b32_e32 v101, 0xffff0000, v113
	v_and_b32_e32 v100, 0xffff0000, v112
	s_waitcnt vmcnt(1)
	v_mov_b32_e32 v102, v74
	v_mov_b32_e32 v103, v76
	v_mov_b32_e32 v76, v75
	s_waitcnt vmcnt(0)
	v_mov_b32_e32 v74, v78
	v_mov_b32_e32 v75, v80
	v_mov_b32_e32 v80, v79
	v_pk_mul_f32 v[78:79], v[82:83], v[102:103]
	v_pk_mul_f32 v[76:77], v[88:89], v[76:77]
	v_pk_mul_f32 v[74:75], v[86:87], v[74:75]
	v_pk_mul_f32 v[78:79], v[78:79], v[94:95]
	v_pk_mul_f32 v[76:77], v[76:77], v[96:97]
	v_pk_mul_f32 v[80:81], v[84:85], v[80:81]
	v_pk_mul_f32 v[82:83], v[74:75], v[98:99]
	v_and_b32_sdwa v75, v78, v169 dst_sel:DWORD dst_unused:UNUSED_PAD src0_sel:WORD_1 src1_sel:DWORD
	v_and_b32_sdwa v84, v77, v169 dst_sel:DWORD dst_unused:UNUSED_PAD src0_sel:WORD_1 src1_sel:DWORD
	v_and_b32_sdwa v85, v76, v169 dst_sel:DWORD dst_unused:UNUSED_PAD src0_sel:WORD_1 src1_sel:DWORD
	v_and_b32_sdwa v74, v79, v169 dst_sel:DWORD dst_unused:UNUSED_PAD src0_sel:WORD_1 src1_sel:DWORD
	v_add3_u32 v78, v78, v75, s33
	v_add3_u32 v75, v77, v84, s33
	v_add3_u32 v76, v76, v85, s33
	v_pk_mul_f32 v[80:81], v[80:81], v[100:101]
	v_add3_u32 v74, v79, v74, s33
	v_and_b32_e32 v75, 0xffff0000, v75
	v_and_b32_e32 v76, 0xffff0000, v76
	v_or_b32_sdwa v75, v75, v74 dst_sel:DWORD dst_unused:UNUSED_PAD src0_sel:DWORD src1_sel:WORD_1
	v_or_b32_sdwa v74, v76, v78 dst_sel:DWORD dst_unused:UNUSED_PAD src0_sel:DWORD src1_sel:WORD_1
	v_and_b32_sdwa v78, v81, v169 dst_sel:DWORD dst_unused:UNUSED_PAD src0_sel:WORD_1 src1_sel:DWORD
	v_and_b32_sdwa v79, v80, v169 dst_sel:DWORD dst_unused:UNUSED_PAD src0_sel:WORD_1 src1_sel:DWORD
	v_and_b32_sdwa v86, v83, v169 dst_sel:DWORD dst_unused:UNUSED_PAD src0_sel:WORD_1 src1_sel:DWORD
	v_and_b32_sdwa v76, v82, v169 dst_sel:DWORD dst_unused:UNUSED_PAD src0_sel:WORD_1 src1_sel:DWORD
	v_add3_u32 v78, v81, v78, s33
	v_add3_u32 v79, v80, v79, s33
	v_add3_u32 v76, v82, v76, s33
	v_add3_u32 v77, v83, v86, s33
	v_and_b32_e32 v78, 0xffff0000, v78
	v_and_b32_e32 v79, 0xffff0000, v79
	v_or_b32_sdwa v77, v78, v77 dst_sel:DWORD dst_unused:UNUSED_PAD src0_sel:DWORD src1_sel:WORD_1
	v_or_b32_sdwa v76, v79, v76 dst_sel:DWORD dst_unused:UNUSED_PAD src0_sel:DWORD src1_sel:WORD_1
	global_store_dwordx4 v[90:91], v[74:77], off
	global_load_dwordx4 v[74:77], v[128:129], off offset:96
	s_nop 0
	global_load_dwordx4 v[78:81], v[128:129], off offset:112
	v_mov_b32_e32 v94, v66
	v_mov_b32_e32 v95, v68
	v_mov_b32_e32 v66, v67
	v_mov_b32_e32 v67, v69
	v_mov_b32_e32 v68, v70
	v_mov_b32_e32 v69, v72
	v_mov_b32_e32 v70, v71
	v_mov_b32_e32 v71, v73
	v_pk_mul_f32 v[72:73], v[94:95], v[92:93] op_sel_hi:[1,0]
	v_pk_mul_f32 v[66:67], v[66:67], v[92:93] op_sel_hi:[1,0]
	v_pk_mul_f32 v[68:69], v[68:69], v[92:93] op_sel_hi:[1,0]
	v_pk_mul_f32 v[70:71], v[70:71], v[92:93] op_sel_hi:[1,0]
	v_and_b32_e32 v85, 0xffff0000, v107
	v_and_b32_e32 v84, 0xffff0000, v106
	v_and_b32_e32 v89, 0xffff0000, v109
	v_and_b32_e32 v88, 0xffff0000, v108
	v_lshlrev_b32_e32 v83, 16, v107
	v_lshlrev_b32_e32 v82, 16, v106
	v_lshlrev_b32_e32 v87, 16, v109
	v_lshlrev_b32_e32 v86, 16, v108
	s_waitcnt vmcnt(1)
	v_mov_b32_e32 v93, v76
	v_mov_b32_e32 v76, v75
	s_waitcnt vmcnt(0)
	v_mov_b32_e32 v75, v80
	v_mov_b32_e32 v80, v79
	v_mov_b32_e32 v92, v74
	v_mov_b32_e32 v74, v78
	v_pk_mul_f32 v[66:67], v[66:67], v[76:77]
	v_pk_mul_f32 v[70:71], v[70:71], v[80:81]
	v_pk_mul_f32 v[72:73], v[72:73], v[92:93]
	v_pk_mul_f32 v[68:69], v[68:69], v[74:75]
	v_pk_mul_f32 v[66:67], v[66:67], v[84:85]
	v_pk_mul_f32 v[70:71], v[70:71], v[88:89]
	v_pk_mul_f32 v[72:73], v[72:73], v[82:83]
	v_pk_mul_f32 v[68:69], v[68:69], v[86:87]
	v_and_b32_sdwa v76, v67, v169 dst_sel:DWORD dst_unused:UNUSED_PAD src0_sel:WORD_1 src1_sel:DWORD
	v_and_b32_sdwa v77, v66, v169 dst_sel:DWORD dst_unused:UNUSED_PAD src0_sel:WORD_1 src1_sel:DWORD
	v_and_b32_sdwa v80, v71, v169 dst_sel:DWORD dst_unused:UNUSED_PAD src0_sel:WORD_1 src1_sel:DWORD
	v_and_b32_sdwa v81, v70, v169 dst_sel:DWORD dst_unused:UNUSED_PAD src0_sel:WORD_1 src1_sel:DWORD
	v_and_b32_sdwa v74, v73, v169 dst_sel:DWORD dst_unused:UNUSED_PAD src0_sel:WORD_1 src1_sel:DWORD
	v_and_b32_sdwa v75, v72, v169 dst_sel:DWORD dst_unused:UNUSED_PAD src0_sel:WORD_1 src1_sel:DWORD
	v_and_b32_sdwa v78, v69, v169 dst_sel:DWORD dst_unused:UNUSED_PAD src0_sel:WORD_1 src1_sel:DWORD
	v_and_b32_sdwa v79, v68, v169 dst_sel:DWORD dst_unused:UNUSED_PAD src0_sel:WORD_1 src1_sel:DWORD
	v_add3_u32 v67, v67, v76, s33
	v_add3_u32 v66, v66, v77, s33
	v_add3_u32 v71, v71, v80, s33
	v_add3_u32 v70, v70, v81, s33
	v_add3_u32 v72, v72, v75, s33
	v_add3_u32 v73, v73, v74, s33
	v_add3_u32 v68, v68, v79, s33
	v_add3_u32 v69, v69, v78, s33
	v_and_b32_e32 v67, 0xffff0000, v67
	v_and_b32_e32 v66, 0xffff0000, v66
	v_and_b32_e32 v71, 0xffff0000, v71
	v_and_b32_e32 v70, 0xffff0000, v70
	v_or_b32_sdwa v67, v67, v73 dst_sel:DWORD dst_unused:UNUSED_PAD src0_sel:DWORD src1_sel:WORD_1
	v_or_b32_sdwa v66, v66, v72 dst_sel:DWORD dst_unused:UNUSED_PAD src0_sel:DWORD src1_sel:WORD_1
	v_or_b32_sdwa v69, v71, v69 dst_sel:DWORD dst_unused:UNUSED_PAD src0_sel:DWORD src1_sel:WORD_1
	v_or_b32_sdwa v68, v70, v68 dst_sel:DWORD dst_unused:UNUSED_PAD src0_sel:DWORD src1_sel:WORD_1
	global_store_dwordx4 v[90:91], v[66:69], off offset:16
	s_cbranch_scc1 .LBB0_167
.LBB0_176:
	v_lshl_add_u64 v[90:91], s[82:83], 0, v[140:141]
	s_mov_b32 s42, 0x12bc0000
	v_add_co_u32_e32 v66, vcc, s42, v90
	s_mov_b32 s42, 0x12bc4000
	s_nop 0
	v_addc_co_u32_e32 v67, vcc, 0, v91, vcc
	v_add_co_u32_e32 v70, vcc, s42, v90
	s_mov_b32 s42, 0x12bc8000
	s_nop 0
	v_addc_co_u32_e32 v71, vcc, 0, v91, vcc
	v_add_co_u32_e32 v74, vcc, s42, v90
	s_mov_b32 s42, 0x12bcc000
	s_nop 0
	v_addc_co_u32_e32 v75, vcc, 0, v91, vcc
	v_add_co_u32_e32 v78, vcc, s42, v90
	s_mov_b32 s42, 0x12bd0000
	s_nop 0
	v_addc_co_u32_e32 v79, vcc, 0, v91, vcc
	v_add_co_u32_e32 v82, vcc, s42, v90
	s_mov_b32 s42, 0x12bd4000
	s_nop 0
	v_addc_co_u32_e32 v83, vcc, 0, v91, vcc
	v_add_co_u32_e32 v86, vcc, s42, v90
	s_mov_b32 s42, 0x12bd8000
	s_nop 0
	v_addc_co_u32_e32 v87, vcc, 0, v91, vcc
	v_add_co_u32_e32 v92, vcc, s42, v90
	s_mov_b32 s42, 0x12bdc000
	s_nop 0
	v_addc_co_u32_e32 v93, vcc, 0, v91, vcc
	v_add_co_u32_e32 v94, vcc, s42, v90
	v_lshl_add_u64 v[106:107], s[82:83], 0, v[138:139]
	s_nop 0
	v_addc_co_u32_e32 v95, vcc, 0, v91, vcc
	s_mov_b32 s42, 0x10bc0000
	v_add_co_u32_e32 v98, vcc, s42, v106
	s_mov_b32 s42, 0x10bc4000
	s_nop 0
	v_addc_co_u32_e32 v99, vcc, 0, v107, vcc
	v_add_co_u32_e32 v102, vcc, s42, v106
	s_mov_b32 s42, 0x10bc8000
	s_nop 0
	v_addc_co_u32_e32 v103, vcc, 0, v107, vcc
	v_add_co_u32_e32 v108, vcc, s42, v106
	s_mov_b32 s42, 0x10bcc000
	s_nop 0
	v_addc_co_u32_e32 v109, vcc, 0, v107, vcc
	v_add_co_u32_e32 v106, vcc, s42, v106
	s_nop 1
	v_addc_co_u32_e32 v107, vcc, 0, v107, vcc
	s_barrier
	global_load_dwordx4 v[66:69], v[66:67], off offset:256
	s_nop 0
	global_load_dwordx4 v[70:73], v[70:71], off offset:256
	s_nop 0
	global_load_dwordx4 v[74:77], v[74:75], off offset:256
	s_nop 0
	global_load_dwordx4 v[78:81], v[78:79], off offset:256
	s_nop 0
	global_load_dwordx4 v[82:85], v[82:83], off offset:256
	s_nop 0
	global_load_dwordx4 v[86:89], v[86:87], off offset:256
	s_nop 0
	global_load_dwordx4 v[90:93], v[92:93], off offset:256
	s_nop 0
	global_load_dwordx4 v[94:97], v[94:95], off offset:256
	s_nop 0
	global_load_dwordx4 v[98:101], v[98:99], off offset:256
	s_nop 0
	global_load_dwordx4 v[102:105], v[102:103], off offset:256
	s_nop 0
	global_load_dwordx4 v[122:125], v[108:109], off offset:256
	global_load_dwordx4 v[176:179], v[106:107], off offset:256
	v_lshl_add_u64 v[106:107], s[82:83], 0, v[142:143]
	s_mov_b32 s42, 0x16bc0000
	v_add_co_u32_e32 v108, vcc, s42, v106
	s_mov_b64 s[42:43], 0x16bc0100
	s_nop 0
	v_addc_co_u32_e32 v109, vcc, 0, v107, vcc
	global_load_dwordx4 v[180:183], v[108:109], off offset:256
	v_lshl_add_u64 v[108:109], v[106:107], 0, s[42:43]
	global_load_dwordx4 v[184:187], v[108:109], off offset:16
	global_load_dwordx4 v[188:191], v[108:109], off offset:32
	global_load_dwordx4 v[192:195], v[108:109], off offset:48
	s_mov_b64 s[42:43], 0x18bc0100
	v_lshl_add_u64 v[114:115], v[106:107], 0, s[42:43]
	s_mov_b32 s42, 0x18bc0000
	v_add_co_u32_e32 v106, vcc, s42, v106
	s_nop 1
	v_addc_co_u32_e32 v107, vcc, 0, v107, vcc
	global_load_dwordx4 v[118:121], v[106:107], off offset:256
	s_nop 0
	global_load_dwordx4 v[106:109], v[114:115], off offset:48
	global_load_dwordx4 v[110:113], v[114:115], off offset:32
	s_nop 0
	global_load_dwordx4 v[114:117], v[114:115], off offset:16
	s_waitcnt vmcnt(19)
	ds_write_b128 v1, v[66:69]
	s_waitcnt vmcnt(18)
	ds_write_b128 v1, v[70:73] offset:4096
	s_waitcnt vmcnt(17)
	ds_write_b128 v1, v[74:77] offset:8192
	s_waitcnt vmcnt(16)
	ds_write_b128 v1, v[78:81] offset:12288
	s_waitcnt vmcnt(15)
	ds_write_b128 v1, v[82:85] offset:16384
	s_waitcnt vmcnt(14)
	ds_write_b128 v1, v[86:89] offset:20480
	s_waitcnt vmcnt(13)
	ds_write_b128 v1, v[90:93] offset:24576
	s_waitcnt vmcnt(12)
	ds_write_b128 v1, v[94:97] offset:28672
	s_waitcnt vmcnt(11)
	ds_write_b128 v146, v[98:101] offset:34816
	s_waitcnt vmcnt(10)
	ds_write_b128 v146, v[102:105] offset:38912
	s_waitcnt vmcnt(9)
	ds_write_b128 v146, v[122:125] offset:43008
	s_waitcnt vmcnt(8)
	ds_write_b128 v146, v[176:179] offset:47104
	s_waitcnt vmcnt(7)
	ds_write_b16 v148, v180 offset:53248
	ds_write_b16_d16_hi v148, v180 offset:53392
	ds_write_b16 v148, v181 offset:53536
	ds_write_b16_d16_hi v148, v181 offset:53680
	ds_write_b16 v148, v182 offset:53824
	ds_write_b16_d16_hi v148, v182 offset:53968
	ds_write_b16 v148, v183 offset:54112
	ds_write_b16_d16_hi v148, v183 offset:54256
	s_waitcnt vmcnt(6)
	ds_write_b16 v148, v184 offset:54400
	ds_write_b16_d16_hi v148, v184 offset:54544
	ds_write_b16 v148, v185 offset:54688
	ds_write_b16_d16_hi v148, v185 offset:54832
	ds_write_b16 v148, v186 offset:54976
	ds_write_b16_d16_hi v148, v186 offset:55120
	ds_write_b16 v148, v187 offset:55264
	ds_write_b16_d16_hi v148, v187 offset:55408
	s_waitcnt vmcnt(5)
	ds_write_b16 v148, v188 offset:55552
	ds_write_b16_d16_hi v148, v188 offset:55696
	ds_write_b16 v148, v189 offset:55840
	ds_write_b16_d16_hi v148, v189 offset:55984
	ds_write_b16 v148, v190 offset:56128
	ds_write_b16_d16_hi v148, v190 offset:56272
	ds_write_b16 v148, v191 offset:56416
	ds_write_b16_d16_hi v148, v191 offset:56560
	s_waitcnt vmcnt(4)
	ds_write_b16 v148, v192 offset:56704
	ds_write_b16_d16_hi v148, v192 offset:56848
	ds_write_b16 v148, v193 offset:56992
	ds_write_b16_d16_hi v148, v193 offset:57136
	ds_write_b16 v148, v194 offset:57280
	ds_write_b16_d16_hi v148, v194 offset:57424
	ds_write_b16 v148, v195 offset:57568
	ds_write_b16_d16_hi v148, v195 offset:57712
	s_waitcnt lgkmcnt(0)
	v_and_b32_e32 v238, 7, v147
	v_lshlrev_b32_e32 v238, 14, v238
	v_add_u32_e32 v238, 0x12be0100, v238
	v_mov_b32_e32 v239, 0
	v_lshl_add_u64 v[240:241], s[82:83], 0, v[140:141]
	v_lshl_add_u64 v[240:241], v[240:241], 0, v[238:239]
	global_load_dword v236, v[240:241], off
	v_and_b32_e32 v238, 3, v147
	v_lshlrev_b32_e32 v238, 14, v238
	v_add_u32_e32 v238, 0x10bd0100, v238
	v_lshl_add_u64 v[242:243], s[82:83], 0, v[138:139]
	v_lshl_add_u64 v[242:243], v[242:243], 0, v[238:239]
	global_load_dword v236, v[242:243], off
	v_lshl_add_u64 v[244:245], s[82:83], 0, v[142:143]
	v_mov_b32_e32 v238, 0x16bd0100
	v_lshl_add_u64 v[246:247], v[244:245], 0, v[238:239]
	global_load_dword v236, v[246:247], off
	v_mov_b32_e32 v238, 0x18bd0100
	v_lshl_add_u64 v[246:247], v[244:245], 0, v[238:239]
	global_load_dword v236, v[246:247], off
	s_barrier
	ds_read2st64_b32 v[96:97], v159 offset1:2
	ds_read2st64_b32 v[94:95], v159 offset0:4 offset1:6
	ds_read2st64_b32 v[92:93], v159 offset0:8 offset1:10
	ds_read2st64_b32 v[90:91], v159 offset0:12 offset1:14
	ds_read2st64_b32 v[88:89], v159 offset0:16 offset1:18
	ds_read_u16 v194, v160 offset:34816
	ds_read_u16 v193, v160 offset:35072
	ds_read_u16 v192, v160 offset:35328
	ds_read_u16 v191, v160 offset:35584
	ds_read_u16 v190, v160 offset:35840
	ds_read_u16 v189, v160 offset:36096
	ds_read_u16 v188, v160 offset:36352
	ds_read_u16 v186, v160 offset:36608
	s_waitcnt lgkmcnt(12)
	v_add_f32_e32 v66, 0, v96
	v_add_f32_e32 v66, v66, v97
	s_waitcnt lgkmcnt(11)
	v_add_f32_e32 v66, v66, v94
	v_add_f32_e32 v66, v66, v95
	s_waitcnt lgkmcnt(10)
	v_add_f32_e32 v66, v66, v92
	v_add_f32_e32 v66, v66, v93
	ds_read2st64_b32 v[86:87], v159 offset0:20 offset1:22
	s_waitcnt lgkmcnt(10)
	v_add_f32_e32 v66, v66, v90
	v_add_f32_e32 v66, v66, v91
	ds_read2st64_b32 v[84:85], v159 offset0:24 offset1:26
	s_waitcnt lgkmcnt(10)
	v_add_f32_e32 v66, v66, v88
	v_add_f32_e32 v66, v66, v89
	ds_read2st64_b32 v[82:83], v159 offset0:28 offset1:30
	s_waitcnt lgkmcnt(2)
	v_add_f32_e32 v66, v66, v86
	v_add_f32_e32 v66, v66, v87
	s_waitcnt lgkmcnt(1)
	v_add_f32_e32 v66, v66, v84
	v_add_f32_e32 v66, v66, v85
	ds_read2st64_b32 v[80:81], v159 offset0:32 offset1:34
	ds_read_u16 v187, v160 offset:36864
	ds_read_u16 v185, v160 offset:37120
	ds_read_u16 v184, v160 offset:37376
	ds_read_u16 v183, v160 offset:37632
	ds_read_u16 v182, v160 offset:37888
	ds_read_u16 v181, v160 offset:38144
	ds_read_u16 v180, v160 offset:38400
	ds_read_u16 v178, v160 offset:38656
	ds_read2st64_b32 v[78:79], v159 offset0:36 offset1:38
	s_waitcnt lgkmcnt(10)
	v_add_f32_e32 v66, v66, v82
	v_add_f32_e32 v66, v66, v83
	ds_read2st64_b32 v[76:77], v159 offset0:40 offset1:42
	s_waitcnt lgkmcnt(10)
	v_add_f32_e32 v66, v66, v80
	v_add_f32_e32 v66, v66, v81
	ds_read2st64_b32 v[74:75], v159 offset0:44 offset1:46
	s_waitcnt lgkmcnt(2)
	v_add_f32_e32 v66, v66, v78
	v_add_f32_e32 v66, v66, v79
	s_waitcnt lgkmcnt(1)
	v_add_f32_e32 v66, v66, v76
	v_add_f32_e32 v66, v66, v77
	ds_read2st64_b32 v[72:73], v159 offset0:48 offset1:50
	ds_read_u16 v179, v160 offset:38912
	ds_read_u16 v177, v160 offset:39168
	ds_read_u16 v176, v160 offset:39424
	ds_read_u16 v175, v160 offset:39680
	ds_read_u16 v125, v160 offset:39936
	ds_read_u16 v124, v160 offset:40192
	ds_read_u16 v123, v160 offset:40448
	ds_read_u16 v105, v160 offset:40704
	ds_read2st64_b32 v[70:71], v159 offset0:52 offset1:54
	s_waitcnt lgkmcnt(10)
	v_add_f32_e32 v66, v66, v74
	v_add_f32_e32 v66, v66, v75
	ds_read2st64_b32 v[68:69], v159 offset0:56 offset1:58
	s_waitcnt lgkmcnt(10)
	v_add_f32_e32 v66, v66, v72
	v_add_f32_e32 v98, v66, v73
	ds_read2st64_b32 v[66:67], v159 offset0:60 offset1:62
	s_waitcnt lgkmcnt(2)
	v_add_f32_e32 v98, v98, v70
	v_add_f32_e32 v98, v98, v71
	s_waitcnt lgkmcnt(1)
	v_add_f32_e32 v98, v98, v68
	v_add_f32_e32 v98, v98, v69
	s_waitcnt lgkmcnt(0)
	v_add_f32_e32 v195, v98, v66
	ds_read_u16 v122, v160 offset:40960
	ds_read_u16 v104, v160 offset:41216
	ds_read_u16 v103, v160 offset:41472
	ds_read_u16 v102, v160 offset:41728
	ds_read_u16 v101, v160 offset:41984
	ds_read_u16 v100, v160 offset:42240
	ds_read_u16 v99, v160 offset:42496
	ds_read_u16 v98, v160 offset:42752
	v_add_f32_e32 v195, v195, v67
	ds_write_b32 v150, v195
	s_waitcnt lgkmcnt(0)
	s_barrier
	ds_read_b32 v195, v151
	s_and_saveexec_b64 s[42:43], s[4:5]
	s_cbranch_execz .LBB0_175
	ds_read_b32 v196, v151 offset:512
	s_waitcnt lgkmcnt(0)
	v_add_f32_e32 v196, v195, v196
	v_mul_f32_e32 v196, 0x3fb8aa3b, v196
	v_exp_f32_e32 v196, v196
	ds_write_b32 v158, v196
	s_branch .LBB0_175
